# P9 softmax merged into P8 per workgroup (G==256), one grid barrier dropped; plus gemm256 K-loop reschedule
# speedup vs baseline: 1.0316x; 1.0033x over previous
; #define LAS __attribute__((address_space(3)))
; #define GLDS_STAGE(st, kt_) do { \
;         _Pragma("unroll") for (int i_ = 0; i_ < FI; ++i_) { \
;             glds16(ap + (size_t)(32 * i_) * lda + (kt_) * 64, l3a + (st) + tid * 16 + i_ * 4096); \
;             glds16(bp + (size_t)(32 * i_) * ldb + (kt_) * 64, l3a + (st) + OPB + tid * 16 + i_ * 4096); } } while (0)
; #define GLDS_STAGE(st, kt_) do { \
;         _Pragma("unroll") for (int i_ = 0; i_ < 4; ++i_) { \
;             glds16(ap + (size_t)(64 * i_) * lda + (kt_) * 64, l3a + (st) + tid * 16 + i_ * 8192); \
;             glds16(bp + (size_t)(64 * i_) * ldb + (kt_) * 64, l3a + (st) + 32768 + tid * 16 + i_ * 8192); } } while (0)
; template <int WT, class Epi>
; DEV void gemm_tile(const bf16_t* __restrict__ A, int lda, const bf16_t* __restrict__ Bt, int ldb, int K, unsigned char* lds, const Epi& epi) {
;     ...
;     const int lrow = tid >> 3, lcs = (tid & 7) ^ (lrow & 7);
;     const bf16_t* ap = A + (size_t)lrow * lda + lcs * 8;
;     const bf16_t* bp = Bt + (size_t)lrow * ldb + lcs * 8;
;     const unsigned l3a = (unsigned)(size_t)(LAS unsigned char*)lds;
;     const int nk = K >> 6;
;     ...
;     constexpr int NSTG = 65536 / STB;
; #pragma unroll
;     for (int s_ = 0; s_ < NSTG - 1; ++s_) if (s_ < nk) GLDS_STAGE(s_ * STB, s_);
;     const int aoff = (wr * WT + fr) * 128, boff = OPB + (wc * WT + fr) * 128, sw = fr & 7;
;     int cur = 0, nxt = (NSTG - 1) * STB;
;     for (int kt = 0; kt < nk; ++kt) {
;         if (NSTG == 4 && kt + 2 < nk) { if (FI == 2) asm volatile("s_waitcnt vmcnt(8)" ::: "memory"); else asm volatile("s_waitcnt vmcnt(0)" ::: "memory"); }
;         else asm volatile("s_waitcnt vmcnt(0)" ::: "memory");
;         __syncthreads();
;         if (kt + NSTG - 1 < nk) GLDS_STAGE(nxt, kt + NSTG - 1);
; #pragma unroll
;         for (int kh = 0; kh < 2; ++kh) {
;             bf16x8 af[FI], bfr[FI];
;             const int ch = ((kh * 4 + fq) ^ sw) << 4;
; #pragma unroll
;             for (int i = 0; i < FI; ++i) { af[i] = *(const bf16x8*)(lds + cur + aoff + i * 2048 + ch); bfr[i] = *(const bf16x8*)(lds + cur + boff + i * 2048 + ch); }
; #pragma unroll
;             for (int mi = 0; mi < FI; ++mi)
; #pragma unroll
;                 for (int ni = 0; ni < FI; ++ni) acc[mi][ni] = __builtin_amdgcn_mfma_f32_16x16x32_bf16(bfr[ni], af[mi], acc[mi][ni], 0, 0, 0);
.LBB0_1295:
	s_ashr_i32 s14, s86, 7
	s_lshl_b32 s4, s86, 6
	s_lshl_b32 s76, s86, 7
	v_mov_b32_e32 v7, v1
	s_lshl_b32 s78, s14, 11
	s_and_b32 s79, s4, 0x780
	s_lshl_b32 s15, s86, 5
	s_and_b32 s77, s76, 0x80
	s_lshl_b32 s14, s14, 8
	s_or_b32 s76, s78, s79
	v_ashrrev_i32_e32 v13, 3, v7
	s_and_b32 s4, s15, 0xc00
	s_or_b32 s14, s14, s77
	v_lshrrev_b32_e32 v4, 4, v7
	v_and_b32_e32 v6, 15, v7
	v_ashrrev_i32_e32 v15, 1, v7
	v_lshlrev_b32_e32 v16, 7, v7
	v_and_b32_e32 v17, 7, v7
	v_mad_i64_i32 v[8:9], s[78:79], s76, v12, v[132:133]
	v_xor_b32_e32 v18, v13, v7
	v_lshlrev_b32_e32 v14, 4, v7
	v_mad_i64_i32 v[10:11], s[78:79], s14, v12, v[168:169]
	v_and_or_b32 v6, v15, s85, v6
	v_and_b32_e32 v15, 0x2780, v16
	v_bitop3_b32 v4, v4, v17, 3 bitop3:0x6c
	v_lshl_add_u64 v[8:9], v[8:9], 0, s[4:5]
	v_lshlrev_b32_e32 v16, 4, v18
	v_add_u32_e32 v19, s80, v14
	v_add_u32_e32 v106, 0x4000, v14
	v_add_u32_e32 v14, s81, v14
	v_lshl_add_u64 v[10:11], v[10:11], 0, s[4:5]
	v_lshlrev_b32_e32 v20, 4, v4
	v_mad_i64_i32 v[8:9], s[86:87], v13, s84, v[8:9]
	v_and_b32_e32 v4, 0x70, v16
	v_add_u32_e32 v18, 0x4000, v19
	v_readfirstlane_b32 s92, v19
	v_readfirstlane_b32 s78, v14
	v_add_u32_e32 v87, s80, v15
	v_mad_i64_i32 v[14:15], s[86:87], v13, s84, v[10:11]
	v_lshl_add_u64 v[10:11], v[8:9], 0, v[4:5]
	s_mov_b32 vcc_lo, m0
	s_mov_b32 m0, s92
	s_nop 0
	global_load_lds_dwordx4 v[10:11], off
	s_mov_b32 m0, vcc_lo
	v_readfirstlane_b32 s14, v18
	v_lshl_add_u64 v[8:9], v[14:15], 0, v[4:5]
	s_mov_b32 vcc_lo, m0
	s_mov_b32 m0, s14
	s_nop 0
	global_load_lds_dwordx4 v[8:9], off
	s_mov_b32 m0, vcc_lo
	v_add_u32_e32 v19, s81, v106
	s_add_i32 s95, s92, 0x1000
	s_add_i32 s15, s14, 0x1000
	s_add_i32 s96, s14, 0x2000
	s_add_i32 s97, s14, 0x3000
	v_lshl_add_u64 v[14:15], v[10:11], 0, s[6:7]
	s_mov_b32 s14, m0
	s_mov_b32 m0, s95
	s_nop 0
	global_load_lds_dwordx4 v[14:15], off
	s_mov_b32 m0, s14
	v_lshl_add_u32 v86, v6, 7, s80
	v_readfirstlane_b32 s88, v19
	v_lshl_add_u64 v[18:19], v[8:9], 0, s[6:7]
	s_mov_b32 s14, m0
	s_mov_b32 m0, s15
	s_nop 0
	global_load_lds_dwordx4 v[18:19], off
	s_mov_b32 m0, s14
	s_add_i32 s94, s92, 0x2000
	v_add_u32_e32 v13, v86, v20
	v_add_u32_e32 v16, v87, v20
	v_lshl_add_u64 v[20:21], v[10:11], 0, s[8:9]
	s_mov_b32 s14, m0
	s_mov_b32 m0, s94
	s_nop 0
	global_load_lds_dwordx4 v[20:21], off
	s_mov_b32 m0, s14
	v_lshl_add_u64 v[22:23], v[8:9], 0, s[8:9]
	s_mov_b32 s14, m0
	s_mov_b32 m0, s96
	s_nop 0
	global_load_lds_dwordx4 v[22:23], off
	s_mov_b32 m0, s14
	s_add_i32 s93, s92, 0x3000
	v_lshl_add_u64 v[24:25], v[10:11], 0, s[10:11]
	s_mov_b32 s14, m0
	s_mov_b32 m0, s93
	s_nop 0
	global_load_lds_dwordx4 v[24:25], off
	s_mov_b32 m0, s14
	v_lshl_add_u64 v[26:27], v[8:9], 0, s[10:11]
	s_mov_b32 s14, m0
	s_mov_b32 m0, s97
	s_nop 0
	global_load_lds_dwordx4 v[26:27], off
	s_mov_b32 m0, s14
	v_lshl_add_u64 v[28:29], v[10:11], 0, s[12:13]
	s_waitcnt vmcnt(0)
	s_barrier
	s_mov_b32 s14, m0
	s_mov_b32 m0, s78
	s_nop 0
	global_load_lds_dwordx4 v[28:29], off
	s_mov_b32 m0, s14
	v_lshl_add_u64 v[30:31], v[8:9], 0, s[12:13]
	s_mov_b32 s14, m0
	s_mov_b32 m0, s88
	s_nop 0
	global_load_lds_dwordx4 v[30:31], off
	s_mov_b32 m0, s14
	s_add_i32 s87, s78, 0x1000
	v_lshl_add_u64 v[32:33], v[10:11], 0, s[16:17]
	s_mov_b32 s14, m0
	s_mov_b32 m0, s87
	s_nop 0
	global_load_lds_dwordx4 v[32:33], off
	s_mov_b32 m0, s14
	s_add_i32 s91, s88, 0x1000
	v_lshl_add_u64 v[34:35], v[8:9], 0, s[16:17]
	s_mov_b32 s14, m0
	s_mov_b32 m0, s91
	s_nop 0
	global_load_lds_dwordx4 v[34:35], off
	s_mov_b32 m0, s14
	s_add_i32 s86, s78, 0x2000
	v_lshl_add_u64 v[36:37], v[10:11], 0, s[18:19]
	s_mov_b32 s14, m0
	s_mov_b32 m0, s86
	s_nop 0
	global_load_lds_dwordx4 v[36:37], off
	s_mov_b32 m0, s14
	s_add_i32 s90, s88, 0x2000
	v_lshl_add_u64 v[38:39], v[8:9], 0, s[18:19]
	s_mov_b32 s14, m0
	s_mov_b32 m0, s90
	s_nop 0
	global_load_lds_dwordx4 v[38:39], off
	s_mov_b32 m0, s14
	s_add_i32 s79, s78, 0x3000
	v_lshl_add_u64 v[40:41], v[10:11], 0, s[20:21]
	s_mov_b32 s14, m0
	s_mov_b32 m0, s79
	s_nop 0
	global_load_lds_dwordx4 v[40:41], off
	s_mov_b32 m0, s14
	s_add_i32 s89, s88, 0x3000
	v_lshl_add_u64 v[42:43], v[8:9], 0, s[20:21]
	s_mov_b32 s14, m0
	s_mov_b32 m0, s89
	s_nop 0
	global_load_lds_dwordx4 v[42:43], off
	s_mov_b32 m0, s14
	ds_read_b128 v[18:21], v16 offset:16384
	ds_read_b128 v[22:25], v16 offset:18432
	ds_read_b128 v[26:29], v13
	ds_read_b128 v[30:33], v13 offset:2048
	ds_read_b128 v[38:41], v16 offset:20480
	ds_read_b128 v[46:49], v16 offset:22528
	ds_read_b128 v[66:69], v13 offset:4096
	ds_read_b128 v[70:73], v13 offset:6144
	v_bfe_u32 v4, v7, 4, 2
	v_bitop3_b32 v14, v4, v17, 4 bitop3:0x36
	v_lshlrev_b32_e32 v15, 4, v14
	v_add_u32_e32 v14, v86, v15
	v_add_u32_e32 v15, v87, v15
	s_waitcnt lgkmcnt(5)
	v_mfma_f32_16x16x32_bf16 v[34:37], v[18:21], v[26:29], 0
	ds_read_b128 v[86:89], v15 offset:16384
	ds_read_b128 v[90:93], v15 offset:18432
	v_add_u32_e32 v17, s80, v106
	v_lshl_add_u64 v[106:107], v[10:11], 0, s[22:23]
	v_mfma_f32_16x16x32_bf16 v[42:45], v[22:25], v[26:29], 0
	v_readfirstlane_b32 s96, v17
	v_lshl_add_u64 v[108:109], v[8:9], 0, s[22:23]
	v_lshl_add_u64 v[110:111], v[10:11], 0, s[24:25]
	s_waitcnt lgkmcnt(5)
	v_mfma_f32_16x16x32_bf16 v[50:53], v[38:41], v[26:29], 0
	s_add_i32 s97, s96, 0x1000
	v_lshl_add_u64 v[112:113], v[8:9], 0, s[24:25]
	s_add_i32 vcc_lo, s96, 0x2000
	s_waitcnt lgkmcnt(4)
	v_mfma_f32_16x16x32_bf16 v[26:29], v[46:49], v[26:29], 0
	v_lshl_add_u64 v[114:115], v[10:11], 0, s[26:27]
	v_lshl_add_u64 v[116:117], v[8:9], 0, s[26:27]
	v_lshl_add_u64 v[118:119], v[10:11], 0, s[30:31]
	v_mfma_f32_16x16x32_bf16 v[54:57], v[18:21], v[30:33], 0
	s_add_i32 vcc_hi, s96, 0x3000
	v_lshl_add_u64 v[120:121], v[8:9], 0, s[30:31]
	v_and_b32_e32 v7, 64, v7
	v_mfma_f32_16x16x32_bf16 v[58:61], v[22:25], v[30:33], 0
	s_add_i32 s15, s82, s83
	v_mfma_f32_16x16x32_bf16 v[62:65], v[38:41], v[30:33], 0
	v_mfma_f32_16x16x32_bf16 v[30:33], v[46:49], v[30:33], 0
	s_waitcnt lgkmcnt(3)
; #define GLDS_STAGE(st, kt_) do { \
;         _Pragma("unroll") for (int i_ = 0; i_ < FI; ++i_) { \
;             glds16(ap + (size_t)(32 * i_) * lda + (kt_) * 64, l3a + (st) + tid * 16 + i_ * 4096); \
;             glds16(bp + (size_t)(32 * i_) * ldb + (kt_) * 64, l3a + (st) + OPB + tid * 16 + i_ * 4096); } } while (0)
; #define GLDS_STAGE(st, kt_) do { \
;         _Pragma("unroll") for (int i_ = 0; i_ < 4; ++i_) { \
;             glds16(ap + (size_t)(64 * i_) * lda + (kt_) * 64, l3a + (st) + tid * 16 + i_ * 8192); \
;             glds16(bp + (size_t)(64 * i_) * ldb + (kt_) * 64, l3a + (st) + 32768 + tid * 16 + i_ * 8192); } } while (0)
; template <int WT, class Epi>
; DEV void gemm_tile(const bf16_t* __restrict__ A, int lda, const bf16_t* __restrict__ Bt, int ldb, int K, unsigned char* lds, const Epi& epi) {
;     ...
;     for (int kt = 0; kt < nk; ++kt) {
;         if (NSTG == 4 && kt + 2 < nk) { if (FI == 2) asm volatile("s_waitcnt vmcnt(8)" ::: "memory"); else asm volatile("s_waitcnt vmcnt(0)" ::: "memory"); }
;         else asm volatile("s_waitcnt vmcnt(0)" ::: "memory");
;         __syncthreads();
;         if (kt + NSTG - 1 < nk) GLDS_STAGE(nxt, kt + NSTG - 1);
; #pragma unroll
;         for (int kh = 0; kh < 2; ++kh) {
;             bf16x8 af[FI], bfr[FI];
;             const int ch = ((kh * 4 + fq) ^ sw) << 4;
; #pragma unroll
;             for (int i = 0; i < FI; ++i) { af[i] = *(const bf16x8*)(lds + cur + aoff + i * 2048 + ch); bfr[i] = *(const bf16x8*)(lds + cur + boff + i * 2048 + ch); }
; #pragma unroll
;             for (int mi = 0; mi < FI; ++mi)
; #pragma unroll
;                 for (int ni = 0; ni < FI; ++ni) acc[mi][ni] = __builtin_amdgcn_mfma_f32_16x16x32_bf16(bfr[ni], af[mi], acc[mi][ni], 0, 0, 0);
;         }
;         nxt = cur; cur += STB; if (cur == NSTG * STB) cur = 0;
	v_mfma_f32_16x16x32_bf16 v[74:77], v[18:21], v[66:69], 0
	v_mfma_f32_16x16x32_bf16 v[78:81], v[22:25], v[66:69], 0
	v_mfma_f32_16x16x32_bf16 v[82:85], v[38:41], v[66:69], 0
	v_mfma_f32_16x16x32_bf16 v[66:69], v[46:49], v[66:69], 0
	s_waitcnt lgkmcnt(2)
	v_mfma_f32_16x16x32_bf16 v[18:21], v[18:21], v[70:73], 0
	v_mfma_f32_16x16x32_bf16 v[22:25], v[22:25], v[70:73], 0
	v_mfma_f32_16x16x32_bf16 v[38:41], v[38:41], v[70:73], 0
	v_mfma_f32_16x16x32_bf16 v[46:49], v[46:49], v[70:73], 0
	ds_read_b128 v[70:73], v14
	ds_read_b128 v[94:97], v14 offset:2048
	ds_read_b128 v[98:101], v15 offset:20480
	ds_read_b128 v[102:105], v15 offset:22528
	s_waitcnt lgkmcnt(3)
	v_mfma_f32_16x16x32_bf16 v[34:37], v[86:89], v[70:73], v[34:37]
	v_mfma_f32_16x16x32_bf16 v[42:45], v[90:93], v[70:73], v[42:45]
	s_waitcnt lgkmcnt(1)
	v_mfma_f32_16x16x32_bf16 v[50:53], v[98:101], v[70:73], v[50:53]
	s_waitcnt lgkmcnt(0)
	v_mfma_f32_16x16x32_bf16 v[26:29], v[102:105], v[70:73], v[26:29]
	v_mfma_f32_16x16x32_bf16 v[54:57], v[86:89], v[94:97], v[54:57]
	v_mfma_f32_16x16x32_bf16 v[58:61], v[90:93], v[94:97], v[58:61]
	v_mfma_f32_16x16x32_bf16 v[62:65], v[98:101], v[94:97], v[62:65]
	v_mfma_f32_16x16x32_bf16 v[30:33], v[102:105], v[94:97], v[30:33]
	ds_read_b128 v[70:73], v14 offset:4096
	ds_read_b128 v[94:97], v14 offset:6144
	s_waitcnt vmcnt(0)
	s_waitcnt lgkmcnt(0)
	s_barrier
	s_mov_b32 s14, m0
	s_mov_b32 m0, s92
	s_nop 0
	global_load_lds_dwordx4 v[106:107], off
	s_mov_b32 m0, s14
	v_mfma_f32_16x16x32_bf16 v[74:77], v[86:89], v[70:73], v[74:77]
	s_mov_b32 s14, m0
	s_mov_b32 m0, s96
	s_nop 0
	global_load_lds_dwordx4 v[108:109], off
	s_mov_b32 m0, s14
	v_lshl_add_u64 v[106:107], v[10:11], 0, s[34:35]
	s_mov_b32 s14, m0
	s_mov_b32 m0, s95
	s_nop 0
	global_load_lds_dwordx4 v[110:111], off
	s_mov_b32 m0, s14
	v_mfma_f32_16x16x32_bf16 v[78:81], v[90:93], v[70:73], v[78:81]
	s_mov_b32 s14, m0
	s_mov_b32 m0, s97
	s_nop 0
	global_load_lds_dwordx4 v[112:113], off
	s_mov_b32 m0, s14
	v_lshl_add_u64 v[108:109], v[8:9], 0, s[34:35]
	s_mov_b32 s14, m0
	s_mov_b32 m0, s94
	s_nop 0
	global_load_lds_dwordx4 v[114:115], off
	s_mov_b32 m0, s14
	v_mfma_f32_16x16x32_bf16 v[82:85], v[98:101], v[70:73], v[82:85]
	s_mov_b32 s14, m0
	s_mov_b32 m0, vcc_lo
	s_nop 0
	global_load_lds_dwordx4 v[116:117], off
	s_mov_b32 m0, s14
	v_lshl_add_u64 v[110:111], v[10:11], 0, s[36:37]
	s_mov_b32 s14, m0
	s_mov_b32 m0, s93
	s_nop 0
	global_load_lds_dwordx4 v[118:119], off
	s_mov_b32 m0, s14
	v_mfma_f32_16x16x32_bf16 v[66:69], v[102:105], v[70:73], v[66:69]
	s_mov_b32 s14, m0
	s_mov_b32 m0, vcc_hi
	s_nop 0
	global_load_lds_dwordx4 v[120:121], off
	s_mov_b32 m0, s14
	v_lshl_add_u64 v[112:113], v[8:9], 0, s[36:37]
	v_lshl_add_u64 v[114:115], v[10:11], 0, s[38:39]
	v_mfma_f32_16x16x32_bf16 v[18:21], v[86:89], v[94:97], v[18:21]
	ds_read_b128 v[70:73], v16 offset:49152
	ds_read_b128 v[86:89], v16 offset:51200
	v_lshl_add_u64 v[116:117], v[8:9], 0, s[38:39]
	v_lshl_add_u64 v[118:119], v[10:11], 0, s[40:41]
	v_mfma_f32_16x16x32_bf16 v[22:25], v[90:93], v[94:97], v[22:25]
	v_lshl_add_u64 v[120:121], v[8:9], 0, s[40:41]
	v_mfma_f32_16x16x32_bf16 v[38:41], v[98:101], v[94:97], v[38:41]
	v_mfma_f32_16x16x32_bf16 v[46:49], v[102:105], v[94:97], v[46:49]
	ds_read_b128 v[90:93], v13 offset:32768
	ds_read_b128 v[94:97], v13 offset:34816
	ds_read_b128 v[98:101], v16 offset:53248
	ds_read_b128 v[102:105], v16 offset:55296
	s_waitcnt lgkmcnt(3)
	v_mfma_f32_16x16x32_bf16 v[34:37], v[70:73], v[90:93], v[34:37]
	v_mfma_f32_16x16x32_bf16 v[42:45], v[86:89], v[90:93], v[42:45]
	s_waitcnt lgkmcnt(1)
	v_mfma_f32_16x16x32_bf16 v[50:53], v[98:101], v[90:93], v[50:53]
	s_waitcnt lgkmcnt(0)
	v_mfma_f32_16x16x32_bf16 v[26:29], v[102:105], v[90:93], v[26:29]
	v_mfma_f32_16x16x32_bf16 v[54:57], v[70:73], v[94:97], v[54:57]
	v_mfma_f32_16x16x32_bf16 v[58:61], v[86:89], v[94:97], v[58:61]
	v_mfma_f32_16x16x32_bf16 v[62:65], v[98:101], v[94:97], v[62:65]
	v_mfma_f32_16x16x32_bf16 v[30:33], v[102:105], v[94:97], v[30:33]
	ds_read_b128 v[90:93], v13 offset:36864
	ds_read_b128 v[94:97], v13 offset:38912
	s_waitcnt lgkmcnt(1)
	v_mfma_f32_16x16x32_bf16 v[74:77], v[70:73], v[90:93], v[74:77]
	v_mfma_f32_16x16x32_bf16 v[78:81], v[86:89], v[90:93], v[78:81]
	v_mfma_f32_16x16x32_bf16 v[82:85], v[98:101], v[90:93], v[82:85]
	v_mfma_f32_16x16x32_bf16 v[66:69], v[102:105], v[90:93], v[66:69]
	s_waitcnt lgkmcnt(0)
	v_mfma_f32_16x16x32_bf16 v[18:21], v[70:73], v[94:97], v[18:21]
	v_mfma_f32_16x16x32_bf16 v[22:25], v[86:89], v[94:97], v[22:25]
	ds_read_b128 v[70:73], v15 offset:49152
	ds_read_b128 v[86:89], v15 offset:51200
	v_mfma_f32_16x16x32_bf16 v[38:41], v[98:101], v[94:97], v[38:41]
	v_mfma_f32_16x16x32_bf16 v[46:49], v[102:105], v[94:97], v[46:49]
	ds_read_b128 v[90:93], v14 offset:32768
	ds_read_b128 v[94:97], v14 offset:34816
	ds_read_b128 v[98:101], v15 offset:53248
	ds_read_b128 v[102:105], v15 offset:55296
	s_waitcnt lgkmcnt(3)
	v_mfma_f32_16x16x32_bf16 v[34:37], v[70:73], v[90:93], v[34:37]
	v_mfma_f32_16x16x32_bf16 v[42:45], v[86:89], v[90:93], v[42:45]
	s_waitcnt lgkmcnt(1)
	v_mfma_f32_16x16x32_bf16 v[50:53], v[98:101], v[90:93], v[50:53]
	s_waitcnt lgkmcnt(0)
	v_mfma_f32_16x16x32_bf16 v[26:29], v[102:105], v[90:93], v[26:29]
	v_mfma_f32_16x16x32_bf16 v[54:57], v[70:73], v[94:97], v[54:57]
	v_mfma_f32_16x16x32_bf16 v[58:61], v[86:89], v[94:97], v[58:61]
	v_mfma_f32_16x16x32_bf16 v[62:65], v[98:101], v[94:97], v[62:65]
	v_mfma_f32_16x16x32_bf16 v[30:33], v[102:105], v[94:97], v[30:33]
	ds_read_b128 v[90:93], v14 offset:36864
	ds_read_b128 v[94:97], v14 offset:38912
	s_waitcnt vmcnt(0)
	s_waitcnt lgkmcnt(0)
	s_barrier
; #define GLDS_STAGE(st, kt_) do { \
;         _Pragma("unroll") for (int i_ = 0; i_ < FI; ++i_) { \
;             glds16(ap + (size_t)(32 * i_) * lda + (kt_) * 64, l3a + (st) + tid * 16 + i_ * 4096); \
;             glds16(bp + (size_t)(32 * i_) * ldb + (kt_) * 64, l3a + (st) + OPB + tid * 16 + i_ * 4096); } } while (0)
; #define GLDS_STAGE(st, kt_) do { \
;         _Pragma("unroll") for (int i_ = 0; i_ < 4; ++i_) { \
;             glds16(ap + (size_t)(64 * i_) * lda + (kt_) * 64, l3a + (st) + tid * 16 + i_ * 8192); \
;             glds16(bp + (size_t)(64 * i_) * ldb + (kt_) * 64, l3a + (st) + 32768 + tid * 16 + i_ * 8192); } } while (0)
; template <int WT, class Epi>
; DEV void gemm_tile(const bf16_t* __restrict__ A, int lda, const bf16_t* __restrict__ Bt, int ldb, int K, unsigned char* lds, const Epi& epi) {
;     ...
;     for (int kt = 0; kt < nk; ++kt) {
;         if (NSTG == 4 && kt + 2 < nk) { if (FI == 2) asm volatile("s_waitcnt vmcnt(8)" ::: "memory"); else asm volatile("s_waitcnt vmcnt(0)" ::: "memory"); }
;         else asm volatile("s_waitcnt vmcnt(0)" ::: "memory");
;         __syncthreads();
;         if (kt + NSTG - 1 < nk) GLDS_STAGE(nxt, kt + NSTG - 1);
; #pragma unroll
;         for (int kh = 0; kh < 2; ++kh) {
;             bf16x8 af[FI], bfr[FI];
;             const int ch = ((kh * 4 + fq) ^ sw) << 4;
; #pragma unroll
;             for (int i = 0; i < FI; ++i) { af[i] = *(const bf16x8*)(lds + cur + aoff + i * 2048 + ch); bfr[i] = *(const bf16x8*)(lds + cur + boff + i * 2048 + ch); }
; #pragma unroll
;             for (int mi = 0; mi < FI; ++mi)
; #pragma unroll
;                 for (int ni = 0; ni < FI; ++ni) acc[mi][ni] = __builtin_amdgcn_mfma_f32_16x16x32_bf16(bfr[ni], af[mi], acc[mi][ni], 0, 0, 0);
;         }
;         nxt = cur; cur += STB; if (cur == NSTG * STB) cur = 0;
	s_mov_b32 s14, m0
	s_mov_b32 m0, s78
	s_nop 0
	global_load_lds_dwordx4 v[106:107], off
	s_mov_b32 m0, s14
	v_mfma_f32_16x16x32_bf16 v[74:77], v[70:73], v[90:93], v[74:77]
	s_mov_b32 s14, m0
	s_mov_b32 m0, s88
	s_nop 0
	global_load_lds_dwordx4 v[108:109], off
	s_mov_b32 m0, s14
	v_lshl_add_u64 v[106:107], v[10:11], 0, s[42:43]
	s_mov_b32 s14, m0
	s_mov_b32 m0, s87
	s_nop 0
	global_load_lds_dwordx4 v[110:111], off
	s_mov_b32 m0, s14
	v_mfma_f32_16x16x32_bf16 v[78:81], v[86:89], v[90:93], v[78:81]
	s_mov_b32 s14, m0
	s_mov_b32 m0, s91
	s_nop 0
	global_load_lds_dwordx4 v[112:113], off
	s_mov_b32 m0, s14
	v_lshl_add_u64 v[108:109], v[8:9], 0, s[42:43]
	s_mov_b32 s14, m0
	s_mov_b32 m0, s86
	s_nop 0
	global_load_lds_dwordx4 v[114:115], off
	s_mov_b32 m0, s14
	v_mfma_f32_16x16x32_bf16 v[82:85], v[98:101], v[90:93], v[82:85]
	s_mov_b32 s14, m0
	s_mov_b32 m0, s90
	s_nop 0
	global_load_lds_dwordx4 v[116:117], off
	s_mov_b32 m0, s14
	v_lshl_add_u64 v[110:111], v[10:11], 0, s[44:45]
	s_mov_b32 s14, m0
	s_mov_b32 m0, s79
	s_nop 0
	global_load_lds_dwordx4 v[118:119], off
	s_mov_b32 m0, s14
	v_mfma_f32_16x16x32_bf16 v[66:69], v[102:105], v[90:93], v[66:69]
	s_mov_b32 s14, m0
	s_mov_b32 m0, s89
	s_nop 0
	global_load_lds_dwordx4 v[120:121], off
	s_mov_b32 m0, s14
	v_lshl_add_u64 v[112:113], v[8:9], 0, s[44:45]
	v_lshl_add_u64 v[114:115], v[10:11], 0, s[46:47]
	v_mfma_f32_16x16x32_bf16 v[18:21], v[70:73], v[94:97], v[18:21]
	v_lshl_add_u64 v[116:117], v[8:9], 0, s[46:47]
	v_lshl_add_u64 v[118:119], v[10:11], 0, s[48:49]
	v_lshl_add_u64 v[120:121], v[8:9], 0, s[48:49]
	v_mfma_f32_16x16x32_bf16 v[22:25], v[86:89], v[94:97], v[22:25]
	ds_read_b128 v[70:73], v16 offset:16384
	ds_read_b128 v[86:89], v16 offset:18432
	v_mfma_f32_16x16x32_bf16 v[38:41], v[98:101], v[94:97], v[38:41]
	v_mfma_f32_16x16x32_bf16 v[46:49], v[102:105], v[94:97], v[46:49]
	ds_read_b128 v[90:93], v13
	ds_read_b128 v[94:97], v13 offset:2048
	ds_read_b128 v[98:101], v16 offset:20480
	ds_read_b128 v[102:105], v16 offset:22528
	s_waitcnt lgkmcnt(3)
	v_mfma_f32_16x16x32_bf16 v[34:37], v[70:73], v[90:93], v[34:37]
	v_mfma_f32_16x16x32_bf16 v[42:45], v[86:89], v[90:93], v[42:45]
	s_waitcnt lgkmcnt(1)
	v_mfma_f32_16x16x32_bf16 v[50:53], v[98:101], v[90:93], v[50:53]
	s_waitcnt lgkmcnt(0)
	v_mfma_f32_16x16x32_bf16 v[26:29], v[102:105], v[90:93], v[26:29]
	v_mfma_f32_16x16x32_bf16 v[54:57], v[70:73], v[94:97], v[54:57]
	v_mfma_f32_16x16x32_bf16 v[58:61], v[86:89], v[94:97], v[58:61]
	v_mfma_f32_16x16x32_bf16 v[62:65], v[98:101], v[94:97], v[62:65]
	v_mfma_f32_16x16x32_bf16 v[30:33], v[102:105], v[94:97], v[30:33]
	ds_read_b128 v[90:93], v13 offset:4096
	ds_read_b128 v[94:97], v13 offset:6144
	s_waitcnt lgkmcnt(1)
	v_mfma_f32_16x16x32_bf16 v[74:77], v[70:73], v[90:93], v[74:77]
	v_mfma_f32_16x16x32_bf16 v[78:81], v[86:89], v[90:93], v[78:81]
	v_mfma_f32_16x16x32_bf16 v[82:85], v[98:101], v[90:93], v[82:85]
	v_mfma_f32_16x16x32_bf16 v[66:69], v[102:105], v[90:93], v[66:69]
	s_waitcnt lgkmcnt(0)
	v_mfma_f32_16x16x32_bf16 v[18:21], v[70:73], v[94:97], v[18:21]
	v_mfma_f32_16x16x32_bf16 v[22:25], v[86:89], v[94:97], v[22:25]
	ds_read_b128 v[70:73], v15 offset:16384
	ds_read_b128 v[86:89], v15 offset:18432
	v_mfma_f32_16x16x32_bf16 v[38:41], v[98:101], v[94:97], v[38:41]
	v_mfma_f32_16x16x32_bf16 v[46:49], v[102:105], v[94:97], v[46:49]
	ds_read_b128 v[90:93], v14
	ds_read_b128 v[94:97], v14 offset:2048
	ds_read_b128 v[98:101], v15 offset:20480
	ds_read_b128 v[102:105], v15 offset:22528
	s_waitcnt lgkmcnt(3)
	v_mfma_f32_16x16x32_bf16 v[34:37], v[70:73], v[90:93], v[34:37]
	v_mfma_f32_16x16x32_bf16 v[42:45], v[86:89], v[90:93], v[42:45]
	s_waitcnt lgkmcnt(1)
	v_mfma_f32_16x16x32_bf16 v[50:53], v[98:101], v[90:93], v[50:53]
	s_waitcnt lgkmcnt(0)
	v_mfma_f32_16x16x32_bf16 v[26:29], v[102:105], v[90:93], v[26:29]
	v_mfma_f32_16x16x32_bf16 v[54:57], v[70:73], v[94:97], v[54:57]
	v_mfma_f32_16x16x32_bf16 v[58:61], v[86:89], v[94:97], v[58:61]
	v_mfma_f32_16x16x32_bf16 v[62:65], v[98:101], v[94:97], v[62:65]
	v_mfma_f32_16x16x32_bf16 v[30:33], v[102:105], v[94:97], v[30:33]
	ds_read_b128 v[90:93], v14 offset:4096
	ds_read_b128 v[94:97], v14 offset:6144
	s_waitcnt vmcnt(0)
	s_waitcnt lgkmcnt(0)
	s_barrier
	s_mov_b32 s14, m0
	s_mov_b32 m0, s92
	s_nop 0
	global_load_lds_dwordx4 v[106:107], off
	s_mov_b32 m0, s14
	v_mfma_f32_16x16x32_bf16 v[74:77], v[70:73], v[90:93], v[74:77]
	s_mov_b32 s14, m0
	s_mov_b32 m0, s96
	s_nop 0
	global_load_lds_dwordx4 v[108:109], off
	s_mov_b32 m0, s14
	v_lshl_add_u64 v[106:107], v[10:11], 0, s[50:51]
	s_mov_b32 s14, m0
	s_mov_b32 m0, s95
	s_nop 0
	global_load_lds_dwordx4 v[110:111], off
	s_mov_b32 m0, s14
	v_mfma_f32_16x16x32_bf16 v[78:81], v[86:89], v[90:93], v[78:81]
	s_mov_b32 s14, m0
	s_mov_b32 m0, s97
	s_nop 0
	global_load_lds_dwordx4 v[112:113], off
	s_mov_b32 m0, s14
	v_lshl_add_u64 v[108:109], v[8:9], 0, s[50:51]
	s_mov_b32 s14, m0
	s_mov_b32 m0, s94
	s_nop 0
	global_load_lds_dwordx4 v[114:115], off
	s_mov_b32 m0, s14
	v_mfma_f32_16x16x32_bf16 v[82:85], v[98:101], v[90:93], v[82:85]
	s_mov_b32 s14, m0
	s_mov_b32 m0, vcc_lo
	s_nop 0
	global_load_lds_dwordx4 v[116:117], off
	s_mov_b32 m0, s14
	v_lshl_add_u64 v[110:111], v[10:11], 0, s[52:53]
	s_mov_b32 s14, m0
	s_mov_b32 m0, s93
	s_nop 0
	global_load_lds_dwordx4 v[118:119], off
	s_mov_b32 m0, s14
	v_mfma_f32_16x16x32_bf16 v[66:69], v[102:105], v[90:93], v[66:69]
	s_mov_b32 s14, m0
	s_mov_b32 m0, vcc_hi
	s_nop 0
	global_load_lds_dwordx4 v[120:121], off
	s_mov_b32 m0, s14
	v_lshl_add_u64 v[112:113], v[8:9], 0, s[52:53]
	v_lshl_add_u64 v[114:115], v[10:11], 0, s[54:55]
	v_mfma_f32_16x16x32_bf16 v[18:21], v[70:73], v[94:97], v[18:21]
	v_lshl_add_u64 v[116:117], v[8:9], 0, s[54:55]
	v_lshl_add_u64 v[118:119], v[10:11], 0, s[56:57]
	v_lshl_add_u64 v[120:121], v[8:9], 0, s[56:57]
	v_mfma_f32_16x16x32_bf16 v[22:25], v[86:89], v[94:97], v[22:25]
	ds_read_b128 v[70:73], v16 offset:49152
	ds_read_b128 v[86:89], v16 offset:51200
	v_mfma_f32_16x16x32_bf16 v[38:41], v[98:101], v[94:97], v[38:41]
	v_mfma_f32_16x16x32_bf16 v[46:49], v[102:105], v[94:97], v[46:49]
	ds_read_b128 v[90:93], v13 offset:32768
	ds_read_b128 v[94:97], v13 offset:34816
	ds_read_b128 v[98:101], v16 offset:53248
	ds_read_b128 v[102:105], v16 offset:55296
	s_waitcnt lgkmcnt(3)
; #define GLDS_STAGE(st, kt_) do { \
;         _Pragma("unroll") for (int i_ = 0; i_ < FI; ++i_) { \
;             glds16(ap + (size_t)(32 * i_) * lda + (kt_) * 64, l3a + (st) + tid * 16 + i_ * 4096); \
;             glds16(bp + (size_t)(32 * i_) * ldb + (kt_) * 64, l3a + (st) + OPB + tid * 16 + i_ * 4096); } } while (0)
; #define GLDS_STAGE(st, kt_) do { \
;         _Pragma("unroll") for (int i_ = 0; i_ < 4; ++i_) { \
;             glds16(ap + (size_t)(64 * i_) * lda + (kt_) * 64, l3a + (st) + tid * 16 + i_ * 8192); \
;             glds16(bp + (size_t)(64 * i_) * ldb + (kt_) * 64, l3a + (st) + 32768 + tid * 16 + i_ * 8192); } } while (0)
; template <int WT, class Epi>
; DEV void gemm_tile(const bf16_t* __restrict__ A, int lda, const bf16_t* __restrict__ Bt, int ldb, int K, unsigned char* lds, const Epi& epi) {
;     ...
;     for (int kt = 0; kt < nk; ++kt) {
;         if (NSTG == 4 && kt + 2 < nk) { if (FI == 2) asm volatile("s_waitcnt vmcnt(8)" ::: "memory"); else asm volatile("s_waitcnt vmcnt(0)" ::: "memory"); }
;         else asm volatile("s_waitcnt vmcnt(0)" ::: "memory");
;         __syncthreads();
;         if (kt + NSTG - 1 < nk) GLDS_STAGE(nxt, kt + NSTG - 1);
; #pragma unroll
;         for (int kh = 0; kh < 2; ++kh) {
;             bf16x8 af[FI], bfr[FI];
;             const int ch = ((kh * 4 + fq) ^ sw) << 4;
; #pragma unroll
;             for (int i = 0; i < FI; ++i) { af[i] = *(const bf16x8*)(lds + cur + aoff + i * 2048 + ch); bfr[i] = *(const bf16x8*)(lds + cur + boff + i * 2048 + ch); }
; #pragma unroll
;             for (int mi = 0; mi < FI; ++mi)
; #pragma unroll
;                 for (int ni = 0; ni < FI; ++ni) acc[mi][ni] = __builtin_amdgcn_mfma_f32_16x16x32_bf16(bfr[ni], af[mi], acc[mi][ni], 0, 0, 0);
;         }
;         nxt = cur; cur += STB; if (cur == NSTG * STB) cur = 0;
	v_mfma_f32_16x16x32_bf16 v[34:37], v[70:73], v[90:93], v[34:37]
	v_mfma_f32_16x16x32_bf16 v[42:45], v[86:89], v[90:93], v[42:45]
	s_waitcnt lgkmcnt(1)
	v_mfma_f32_16x16x32_bf16 v[50:53], v[98:101], v[90:93], v[50:53]
	s_waitcnt lgkmcnt(0)
	v_mfma_f32_16x16x32_bf16 v[26:29], v[102:105], v[90:93], v[26:29]
	v_mfma_f32_16x16x32_bf16 v[54:57], v[70:73], v[94:97], v[54:57]
	v_mfma_f32_16x16x32_bf16 v[58:61], v[86:89], v[94:97], v[58:61]
	v_mfma_f32_16x16x32_bf16 v[62:65], v[98:101], v[94:97], v[62:65]
	v_mfma_f32_16x16x32_bf16 v[30:33], v[102:105], v[94:97], v[30:33]
	ds_read_b128 v[90:93], v13 offset:36864
	ds_read_b128 v[94:97], v13 offset:38912
	s_waitcnt lgkmcnt(1)
	v_mfma_f32_16x16x32_bf16 v[74:77], v[70:73], v[90:93], v[74:77]
	v_mfma_f32_16x16x32_bf16 v[78:81], v[86:89], v[90:93], v[78:81]
	v_mfma_f32_16x16x32_bf16 v[82:85], v[98:101], v[90:93], v[82:85]
	v_mfma_f32_16x16x32_bf16 v[66:69], v[102:105], v[90:93], v[66:69]
	s_waitcnt lgkmcnt(0)
	v_mfma_f32_16x16x32_bf16 v[18:21], v[70:73], v[94:97], v[18:21]
	v_mfma_f32_16x16x32_bf16 v[22:25], v[86:89], v[94:97], v[22:25]
	ds_read_b128 v[70:73], v15 offset:49152
	ds_read_b128 v[86:89], v15 offset:51200
	v_mfma_f32_16x16x32_bf16 v[38:41], v[98:101], v[94:97], v[38:41]
	v_mfma_f32_16x16x32_bf16 v[46:49], v[102:105], v[94:97], v[46:49]
	ds_read_b128 v[90:93], v14 offset:32768
	ds_read_b128 v[94:97], v14 offset:34816
	ds_read_b128 v[98:101], v15 offset:53248
	ds_read_b128 v[102:105], v15 offset:55296
	s_waitcnt lgkmcnt(3)
	v_mfma_f32_16x16x32_bf16 v[34:37], v[70:73], v[90:93], v[34:37]
	v_mfma_f32_16x16x32_bf16 v[42:45], v[86:89], v[90:93], v[42:45]
	s_waitcnt lgkmcnt(1)
	v_mfma_f32_16x16x32_bf16 v[50:53], v[98:101], v[90:93], v[50:53]
	s_waitcnt lgkmcnt(0)
	v_mfma_f32_16x16x32_bf16 v[26:29], v[102:105], v[90:93], v[26:29]
	v_mfma_f32_16x16x32_bf16 v[54:57], v[70:73], v[94:97], v[54:57]
	v_mfma_f32_16x16x32_bf16 v[58:61], v[86:89], v[94:97], v[58:61]
	v_mfma_f32_16x16x32_bf16 v[62:65], v[98:101], v[94:97], v[62:65]
	v_mfma_f32_16x16x32_bf16 v[30:33], v[102:105], v[94:97], v[30:33]
	ds_read_b128 v[90:93], v14 offset:36864
	ds_read_b128 v[94:97], v14 offset:38912
	s_waitcnt vmcnt(0)
	s_waitcnt lgkmcnt(0)
	s_barrier
	s_mov_b32 s14, m0
	s_mov_b32 m0, s78
	s_nop 0
	global_load_lds_dwordx4 v[106:107], off
	s_mov_b32 m0, s14
	v_mfma_f32_16x16x32_bf16 v[74:77], v[70:73], v[90:93], v[74:77]
	s_mov_b32 s14, m0
	s_mov_b32 m0, s88
	s_nop 0
	global_load_lds_dwordx4 v[108:109], off
	s_mov_b32 m0, s14
	v_lshl_add_u64 v[106:107], v[10:11], 0, s[58:59]
	s_mov_b32 s14, m0
	s_mov_b32 m0, s87
	s_nop 0
	global_load_lds_dwordx4 v[110:111], off
	s_mov_b32 m0, s14
	v_mfma_f32_16x16x32_bf16 v[78:81], v[86:89], v[90:93], v[78:81]
	s_mov_b32 s14, m0
	s_mov_b32 m0, s91
	s_nop 0
	global_load_lds_dwordx4 v[112:113], off
	s_mov_b32 m0, s14
	v_lshl_add_u64 v[108:109], v[8:9], 0, s[58:59]
	s_mov_b32 s14, m0
	s_mov_b32 m0, s86
	s_nop 0
	global_load_lds_dwordx4 v[114:115], off
	s_mov_b32 m0, s14
	v_mfma_f32_16x16x32_bf16 v[82:85], v[98:101], v[90:93], v[82:85]
	s_mov_b32 s14, m0
	s_mov_b32 m0, s90
	s_nop 0
	global_load_lds_dwordx4 v[116:117], off
	s_mov_b32 m0, s14
	v_lshl_add_u64 v[110:111], v[10:11], 0, s[60:61]
	s_mov_b32 s14, m0
	s_mov_b32 m0, s79
	s_nop 0
	global_load_lds_dwordx4 v[118:119], off
	s_mov_b32 m0, s14
	v_mfma_f32_16x16x32_bf16 v[66:69], v[102:105], v[90:93], v[66:69]
	s_mov_b32 s14, m0
	s_mov_b32 m0, s89
	s_nop 0
	global_load_lds_dwordx4 v[120:121], off
	s_mov_b32 m0, s14
	v_lshl_add_u64 v[112:113], v[8:9], 0, s[60:61]
	v_lshl_add_u64 v[114:115], v[10:11], 0, s[62:63]
	v_mfma_f32_16x16x32_bf16 v[18:21], v[70:73], v[94:97], v[18:21]
	v_lshl_add_u64 v[116:117], v[8:9], 0, s[62:63]
	v_lshl_add_u64 v[118:119], v[10:11], 0, s[64:65]
	v_lshl_add_u64 v[120:121], v[8:9], 0, s[64:65]
	v_mfma_f32_16x16x32_bf16 v[22:25], v[86:89], v[94:97], v[22:25]
	ds_read_b128 v[70:73], v16 offset:16384
	ds_read_b128 v[86:89], v16 offset:18432
	v_mfma_f32_16x16x32_bf16 v[38:41], v[98:101], v[94:97], v[38:41]
	v_mfma_f32_16x16x32_bf16 v[46:49], v[102:105], v[94:97], v[46:49]
	ds_read_b128 v[90:93], v13
	ds_read_b128 v[94:97], v13 offset:2048
	ds_read_b128 v[98:101], v16 offset:20480
	ds_read_b128 v[102:105], v16 offset:22528
	s_waitcnt lgkmcnt(3)
	v_mfma_f32_16x16x32_bf16 v[34:37], v[70:73], v[90:93], v[34:37]
	v_mfma_f32_16x16x32_bf16 v[42:45], v[86:89], v[90:93], v[42:45]
	s_waitcnt lgkmcnt(1)
	v_mfma_f32_16x16x32_bf16 v[50:53], v[98:101], v[90:93], v[50:53]
	s_waitcnt lgkmcnt(0)
	v_mfma_f32_16x16x32_bf16 v[26:29], v[102:105], v[90:93], v[26:29]
	v_mfma_f32_16x16x32_bf16 v[54:57], v[70:73], v[94:97], v[54:57]
	v_mfma_f32_16x16x32_bf16 v[58:61], v[86:89], v[94:97], v[58:61]
	v_mfma_f32_16x16x32_bf16 v[62:65], v[98:101], v[94:97], v[62:65]
	v_mfma_f32_16x16x32_bf16 v[30:33], v[102:105], v[94:97], v[30:33]
	ds_read_b128 v[90:93], v13 offset:4096
	ds_read_b128 v[94:97], v13 offset:6144
	s_waitcnt lgkmcnt(1)
	v_mfma_f32_16x16x32_bf16 v[74:77], v[70:73], v[90:93], v[74:77]
	v_mfma_f32_16x16x32_bf16 v[78:81], v[86:89], v[90:93], v[78:81]
	v_mfma_f32_16x16x32_bf16 v[82:85], v[98:101], v[90:93], v[82:85]
	v_mfma_f32_16x16x32_bf16 v[66:69], v[102:105], v[90:93], v[66:69]
	s_waitcnt lgkmcnt(0)
	v_mfma_f32_16x16x32_bf16 v[18:21], v[70:73], v[94:97], v[18:21]
	v_mfma_f32_16x16x32_bf16 v[22:25], v[86:89], v[94:97], v[22:25]
	ds_read_b128 v[70:73], v15 offset:16384
	ds_read_b128 v[86:89], v15 offset:18432
	v_mfma_f32_16x16x32_bf16 v[38:41], v[98:101], v[94:97], v[38:41]
	v_mfma_f32_16x16x32_bf16 v[46:49], v[102:105], v[94:97], v[46:49]
	ds_read_b128 v[90:93], v14
	ds_read_b128 v[94:97], v14 offset:2048
	ds_read_b128 v[98:101], v15 offset:20480
	ds_read_b128 v[102:105], v15 offset:22528
	s_waitcnt lgkmcnt(3)
	v_mfma_f32_16x16x32_bf16 v[34:37], v[70:73], v[90:93], v[34:37]
	v_mfma_f32_16x16x32_bf16 v[42:45], v[86:89], v[90:93], v[42:45]
	s_waitcnt lgkmcnt(1)
	v_mfma_f32_16x16x32_bf16 v[50:53], v[98:101], v[90:93], v[50:53]
	s_waitcnt lgkmcnt(0)
	v_mfma_f32_16x16x32_bf16 v[26:29], v[102:105], v[90:93], v[26:29]
	v_mfma_f32_16x16x32_bf16 v[54:57], v[70:73], v[94:97], v[54:57]
	v_mfma_f32_16x16x32_bf16 v[58:61], v[86:89], v[94:97], v[58:61]
	v_mfma_f32_16x16x32_bf16 v[62:65], v[98:101], v[94:97], v[62:65]
	v_mfma_f32_16x16x32_bf16 v[30:33], v[102:105], v[94:97], v[30:33]
	ds_read_b128 v[90:93], v14 offset:4096
	ds_read_b128 v[94:97], v14 offset:6144
	s_waitcnt vmcnt(0)
	s_waitcnt lgkmcnt(0)
	s_barrier
; #define GLDS_STAGE(st, kt_) do { \
;         _Pragma("unroll") for (int i_ = 0; i_ < FI; ++i_) { \
;             glds16(ap + (size_t)(32 * i_) * lda + (kt_) * 64, l3a + (st) + tid * 16 + i_ * 4096); \
;             glds16(bp + (size_t)(32 * i_) * ldb + (kt_) * 64, l3a + (st) + OPB + tid * 16 + i_ * 4096); } } while (0)
; #define GLDS_STAGE(st, kt_) do { \
;         _Pragma("unroll") for (int i_ = 0; i_ < 4; ++i_) { \
;             glds16(ap + (size_t)(64 * i_) * lda + (kt_) * 64, l3a + (st) + tid * 16 + i_ * 8192); \
;             glds16(bp + (size_t)(64 * i_) * ldb + (kt_) * 64, l3a + (st) + 32768 + tid * 16 + i_ * 8192); } } while (0)
; template <int WT, class Epi>
; DEV void gemm_tile(const bf16_t* __restrict__ A, int lda, const bf16_t* __restrict__ Bt, int ldb, int K, unsigned char* lds, const Epi& epi) {
;     ...
;     for (int kt = 0; kt < nk; ++kt) {
;         if (NSTG == 4 && kt + 2 < nk) { if (FI == 2) asm volatile("s_waitcnt vmcnt(8)" ::: "memory"); else asm volatile("s_waitcnt vmcnt(0)" ::: "memory"); }
;         else asm volatile("s_waitcnt vmcnt(0)" ::: "memory");
;         __syncthreads();
;         if (kt + NSTG - 1 < nk) GLDS_STAGE(nxt, kt + NSTG - 1);
; #pragma unroll
;         for (int kh = 0; kh < 2; ++kh) {
;             bf16x8 af[FI], bfr[FI];
;             const int ch = ((kh * 4 + fq) ^ sw) << 4;
; #pragma unroll
;             for (int i = 0; i < FI; ++i) { af[i] = *(const bf16x8*)(lds + cur + aoff + i * 2048 + ch); bfr[i] = *(const bf16x8*)(lds + cur + boff + i * 2048 + ch); }
; #pragma unroll
;             for (int mi = 0; mi < FI; ++mi)
; #pragma unroll
;                 for (int ni = 0; ni < FI; ++ni) acc[mi][ni] = __builtin_amdgcn_mfma_f32_16x16x32_bf16(bfr[ni], af[mi], acc[mi][ni], 0, 0, 0);
;         }
;         nxt = cur; cur += STB; if (cur == NSTG * STB) cur = 0;
	s_mov_b32 s14, m0
	s_mov_b32 m0, s92
	s_nop 0
	global_load_lds_dwordx4 v[106:107], off
	s_mov_b32 m0, s14
	v_mfma_f32_16x16x32_bf16 v[74:77], v[70:73], v[90:93], v[74:77]
	s_mov_b32 s14, m0
	s_mov_b32 m0, s96
	s_nop 0
	global_load_lds_dwordx4 v[108:109], off
	s_mov_b32 m0, s14
	v_lshl_add_u64 v[106:107], v[10:11], 0, s[66:67]
	s_mov_b32 s14, m0
	s_mov_b32 m0, s95
	s_nop 0
	global_load_lds_dwordx4 v[110:111], off
	s_mov_b32 m0, s14
	v_mfma_f32_16x16x32_bf16 v[78:81], v[86:89], v[90:93], v[78:81]
	s_mov_b32 s14, m0
	s_mov_b32 m0, s97
	s_nop 0
	global_load_lds_dwordx4 v[112:113], off
	s_mov_b32 m0, s14
	v_lshl_add_u64 v[108:109], v[8:9], 0, s[66:67]
	s_mov_b32 s14, m0
	s_mov_b32 m0, s94
	s_nop 0
	global_load_lds_dwordx4 v[114:115], off
	s_mov_b32 m0, s14
	v_mfma_f32_16x16x32_bf16 v[82:85], v[98:101], v[90:93], v[82:85]
	s_mov_b32 s14, m0
	s_mov_b32 m0, vcc_lo
	s_nop 0
	global_load_lds_dwordx4 v[116:117], off
	s_mov_b32 m0, s14
	v_lshl_add_u64 v[110:111], v[10:11], 0, s[68:69]
	s_mov_b32 s14, m0
	s_mov_b32 m0, s93
	s_nop 0
	global_load_lds_dwordx4 v[118:119], off
	s_mov_b32 m0, s14
	v_mfma_f32_16x16x32_bf16 v[66:69], v[102:105], v[90:93], v[66:69]
	s_mov_b32 s14, m0
	s_mov_b32 m0, vcc_hi
	s_nop 0
	global_load_lds_dwordx4 v[120:121], off
	s_mov_b32 m0, s14
	v_lshl_add_u64 v[112:113], v[8:9], 0, s[68:69]
	v_lshl_add_u64 v[114:115], v[10:11], 0, s[70:71]
	v_mfma_f32_16x16x32_bf16 v[18:21], v[70:73], v[94:97], v[18:21]
	v_lshl_add_u64 v[116:117], v[8:9], 0, s[70:71]
	v_lshl_add_u64 v[118:119], v[10:11], 0, s[72:73]
	v_lshl_add_u64 v[120:121], v[8:9], 0, s[72:73]
	v_mfma_f32_16x16x32_bf16 v[22:25], v[86:89], v[94:97], v[22:25]
	ds_read_b128 v[70:73], v16 offset:49152
	ds_read_b128 v[86:89], v16 offset:51200
	v_mfma_f32_16x16x32_bf16 v[38:41], v[98:101], v[94:97], v[38:41]
	v_mfma_f32_16x16x32_bf16 v[46:49], v[102:105], v[94:97], v[46:49]
	ds_read_b128 v[90:93], v13 offset:32768
	ds_read_b128 v[94:97], v13 offset:34816
	ds_read_b128 v[98:101], v16 offset:53248
	ds_read_b128 v[102:105], v16 offset:55296
	s_waitcnt lgkmcnt(3)
	v_mfma_f32_16x16x32_bf16 v[34:37], v[70:73], v[90:93], v[34:37]
	v_mfma_f32_16x16x32_bf16 v[42:45], v[86:89], v[90:93], v[42:45]
	s_waitcnt lgkmcnt(1)
	v_mfma_f32_16x16x32_bf16 v[50:53], v[98:101], v[90:93], v[50:53]
	s_waitcnt lgkmcnt(0)
	v_mfma_f32_16x16x32_bf16 v[26:29], v[102:105], v[90:93], v[26:29]
	v_mfma_f32_16x16x32_bf16 v[54:57], v[70:73], v[94:97], v[54:57]
	v_mfma_f32_16x16x32_bf16 v[58:61], v[86:89], v[94:97], v[58:61]
	v_mfma_f32_16x16x32_bf16 v[62:65], v[98:101], v[94:97], v[62:65]
	v_mfma_f32_16x16x32_bf16 v[30:33], v[102:105], v[94:97], v[30:33]
	ds_read_b128 v[90:93], v13 offset:36864
	ds_read_b128 v[94:97], v13 offset:38912
	s_waitcnt lgkmcnt(1)
	v_mfma_f32_16x16x32_bf16 v[74:77], v[70:73], v[90:93], v[74:77]
	v_mfma_f32_16x16x32_bf16 v[78:81], v[86:89], v[90:93], v[78:81]
	v_mfma_f32_16x16x32_bf16 v[82:85], v[98:101], v[90:93], v[82:85]
	v_mfma_f32_16x16x32_bf16 v[66:69], v[102:105], v[90:93], v[66:69]
	s_waitcnt lgkmcnt(0)
	v_mfma_f32_16x16x32_bf16 v[18:21], v[70:73], v[94:97], v[18:21]
	v_mfma_f32_16x16x32_bf16 v[22:25], v[86:89], v[94:97], v[22:25]
	ds_read_b128 v[70:73], v15 offset:49152
	ds_read_b128 v[86:89], v15 offset:51200
	v_mfma_f32_16x16x32_bf16 v[38:41], v[98:101], v[94:97], v[38:41]
	v_mfma_f32_16x16x32_bf16 v[46:49], v[102:105], v[94:97], v[46:49]
	ds_read_b128 v[90:93], v14 offset:32768
	ds_read_b128 v[94:97], v14 offset:34816
	ds_read_b128 v[98:101], v15 offset:53248
	ds_read_b128 v[102:105], v15 offset:55296
	s_waitcnt lgkmcnt(3)
	v_mfma_f32_16x16x32_bf16 v[34:37], v[70:73], v[90:93], v[34:37]
	v_mfma_f32_16x16x32_bf16 v[42:45], v[86:89], v[90:93], v[42:45]
	s_waitcnt lgkmcnt(1)
	v_mfma_f32_16x16x32_bf16 v[50:53], v[98:101], v[90:93], v[50:53]
	s_waitcnt lgkmcnt(0)
	v_mfma_f32_16x16x32_bf16 v[26:29], v[102:105], v[90:93], v[26:29]
	v_mfma_f32_16x16x32_bf16 v[54:57], v[70:73], v[94:97], v[54:57]
	v_mfma_f32_16x16x32_bf16 v[58:61], v[86:89], v[94:97], v[58:61]
	v_mfma_f32_16x16x32_bf16 v[62:65], v[98:101], v[94:97], v[62:65]
	v_mfma_f32_16x16x32_bf16 v[30:33], v[102:105], v[94:97], v[30:33]
	ds_read_b128 v[90:93], v14 offset:36864
	ds_read_b128 v[94:97], v14 offset:38912
	s_waitcnt vmcnt(0)
	s_waitcnt lgkmcnt(0)
	s_barrier
; #define GLDS_STAGE(st, kt_) do { \
;         _Pragma("unroll") for (int i_ = 0; i_ < FI; ++i_) { \
;             glds16(ap + (size_t)(32 * i_) * lda + (kt_) * 64, l3a + (st) + tid * 16 + i_ * 4096); \
;             glds16(bp + (size_t)(32 * i_) * ldb + (kt_) * 64, l3a + (st) + OPB + tid * 16 + i_ * 4096); } } while (0)
; #define GLDS_STAGE(st, kt_) do { \
;         _Pragma("unroll") for (int i_ = 0; i_ < 4; ++i_) { \
;             glds16(ap + (size_t)(64 * i_) * lda + (kt_) * 64, l3a + (st) + tid * 16 + i_ * 8192); \
;             glds16(bp + (size_t)(64 * i_) * ldb + (kt_) * 64, l3a + (st) + 32768 + tid * 16 + i_ * 8192); } } while (0)
; template <int WT, class Epi>
; DEV void gemm_tile(const bf16_t* __restrict__ A, int lda, const bf16_t* __restrict__ Bt, int ldb, int K, unsigned char* lds, const Epi& epi) {
;     ...
;     for (int kt = 0; kt < nk; ++kt) {
;         if (NSTG == 4 && kt + 2 < nk) { if (FI == 2) asm volatile("s_waitcnt vmcnt(8)" ::: "memory"); else asm volatile("s_waitcnt vmcnt(0)" ::: "memory"); }
;         else asm volatile("s_waitcnt vmcnt(0)" ::: "memory");
;         __syncthreads();
;         if (kt + NSTG - 1 < nk) GLDS_STAGE(nxt, kt + NSTG - 1);
; #pragma unroll
;         for (int kh = 0; kh < 2; ++kh) {
;             bf16x8 af[FI], bfr[FI];
;             const int ch = ((kh * 4 + fq) ^ sw) << 4;
; #pragma unroll
;             for (int i = 0; i < FI; ++i) { af[i] = *(const bf16x8*)(lds + cur + aoff + i * 2048 + ch); bfr[i] = *(const bf16x8*)(lds + cur + boff + i * 2048 + ch); }
; #pragma unroll
;             for (int mi = 0; mi < FI; ++mi)
; #pragma unroll
;                 for (int ni = 0; ni < FI; ++ni) acc[mi][ni] = __builtin_amdgcn_mfma_f32_16x16x32_bf16(bfr[ni], af[mi], acc[mi][ni], 0, 0, 0);
;         }
;         nxt = cur; cur += STB; if (cur == NSTG * STB) cur = 0;
	s_mov_b32 s14, m0
	s_mov_b32 m0, s78
	s_nop 0
	global_load_lds_dwordx4 v[106:107], off
	s_mov_b32 m0, s14
	v_mfma_f32_16x16x32_bf16 v[74:77], v[70:73], v[90:93], v[74:77]
	s_mov_b32 s14, m0
	s_mov_b32 m0, s88
	s_nop 0
	global_load_lds_dwordx4 v[108:109], off
	s_mov_b32 m0, s14
	s_lshl_b32 s78, s77, 2
	s_mov_b32 s14, m0
	s_mov_b32 m0, s87
	s_nop 0
	global_load_lds_dwordx4 v[110:111], off
	s_mov_b32 m0, s14
	v_mfma_f32_16x16x32_bf16 v[78:81], v[86:89], v[90:93], v[78:81]
	s_mov_b32 s14, m0
	s_mov_b32 m0, s91
	s_nop 0
	global_load_lds_dwordx4 v[112:113], off
	s_mov_b32 m0, s14
	s_ashr_i32 s77, s76, 31
	s_mov_b32 s14, m0
	s_mov_b32 m0, s86
	s_nop 0
	global_load_lds_dwordx4 v[114:115], off
	s_mov_b32 m0, s14
	v_mfma_f32_16x16x32_bf16 v[8:11], v[98:101], v[90:93], v[82:85]
	s_mov_b32 s14, m0
	s_mov_b32 m0, s90
	s_nop 0
	global_load_lds_dwordx4 v[116:117], off
	s_mov_b32 m0, s14
	s_lshl_b64 s[76:77], s[76:77], 12
	s_mov_b32 s14, m0
	s_mov_b32 m0, s79
	s_nop 0
	global_load_lds_dwordx4 v[118:119], off
	s_mov_b32 m0, s14
	v_mfma_f32_16x16x32_bf16 v[66:69], v[102:105], v[90:93], v[66:69]
	s_mov_b32 s14, m0
	s_mov_b32 m0, s89
	s_nop 0
	global_load_lds_dwordx4 v[120:121], off
	s_mov_b32 m0, s14
	s_mov_b32 s79, s5
	s_add_i32 s14, s83, s75
	v_mfma_f32_16x16x32_bf16 v[18:21], v[70:73], v[94:97], v[18:21]
	ds_read_b128 v[70:73], v16 offset:16384
	ds_read_b128 v[82:85], v16 offset:18432
	s_min_i32 s86, s15, 0x1ff
	s_mov_b32 s83, s14
	v_mfma_f32_16x16x32_bf16 v[22:25], v[86:89], v[94:97], v[22:25]
	ds_read_b128 v[86:89], v13
	ds_read_b128 v[90:93], v13 offset:2048
	s_cmpk_lt_i32 s14, 0x200
	v_mfma_f32_16x16x32_bf16 v[38:41], v[98:101], v[94:97], v[38:41]
	ds_read_b128 v[98:101], v16 offset:22528
	v_mfma_f32_16x16x32_bf16 v[46:49], v[102:105], v[94:97], v[46:49]
	ds_read_b128 v[94:97], v16 offset:20480
	v_or_b32_e32 v102, 48, v6
	v_lshl_add_u64 v[104:105], v[2:3], 0, s[76:77]
	s_waitcnt lgkmcnt(3)
	v_mfma_f32_16x16x32_bf16 v[34:37], v[70:73], v[86:89], v[34:37]
	v_ashrrev_i32_e32 v103, 31, v102
	v_mfma_f32_16x16x32_bf16 v[42:45], v[82:85], v[86:89], v[42:45]
	s_waitcnt lgkmcnt(0)
	v_mfma_f32_16x16x32_bf16 v[50:53], v[94:97], v[86:89], v[50:53]
	v_mfma_f32_16x16x32_bf16 v[26:29], v[98:101], v[86:89], v[26:29]
	v_mfma_f32_16x16x32_bf16 v[54:57], v[70:73], v[90:93], v[54:57]
	v_mfma_f32_16x16x32_bf16 v[58:61], v[82:85], v[90:93], v[58:61]
	v_mfma_f32_16x16x32_bf16 v[62:65], v[94:97], v[90:93], v[62:65]
	v_mfma_f32_16x16x32_bf16 v[30:33], v[98:101], v[90:93], v[30:33]
	ds_read_b128 v[86:89], v13 offset:4096
	ds_read_b128 v[90:93], v13 offset:6144
	s_waitcnt lgkmcnt(1)
	v_mfma_f32_16x16x32_bf16 v[74:77], v[70:73], v[86:89], v[74:77]
	v_mfma_f32_16x16x32_bf16 v[78:81], v[82:85], v[86:89], v[78:81]
	v_mfma_f32_16x16x32_bf16 v[8:11], v[94:97], v[86:89], v[8:11]
	v_mfma_f32_16x16x32_bf16 v[66:69], v[98:101], v[86:89], v[66:69]
	s_waitcnt lgkmcnt(0)
	v_mfma_f32_16x16x32_bf16 v[18:21], v[70:73], v[90:93], v[18:21]
	v_mfma_f32_16x16x32_bf16 v[22:25], v[82:85], v[90:93], v[22:25]
	ds_read_b128 v[70:73], v15 offset:16384
	ds_read_b128 v[82:85], v15 offset:18432
	v_mfma_f32_16x16x32_bf16 v[38:41], v[94:97], v[90:93], v[38:41]
	v_mfma_f32_16x16x32_bf16 v[46:49], v[98:101], v[90:93], v[46:49]
	ds_read_b128 v[86:89], v14
	ds_read_b128 v[90:93], v14 offset:2048
	ds_read_b128 v[94:97], v15 offset:20480
	ds_read_b128 v[98:101], v15 offset:22528
	s_waitcnt lgkmcnt(3)
	v_mfma_f32_16x16x32_bf16 v[34:37], v[70:73], v[86:89], v[34:37]
	v_mfma_f32_16x16x32_bf16 v[42:45], v[82:85], v[86:89], v[42:45]
	s_waitcnt lgkmcnt(1)
	v_mfma_f32_16x16x32_bf16 v[50:53], v[94:97], v[86:89], v[50:53]
	s_waitcnt lgkmcnt(0)
	v_mfma_f32_16x16x32_bf16 v[26:29], v[98:101], v[86:89], v[26:29]
	v_mfma_f32_16x16x32_bf16 v[54:57], v[70:73], v[90:93], v[54:57]
	v_mfma_f32_16x16x32_bf16 v[58:61], v[82:85], v[90:93], v[58:61]
	v_mfma_f32_16x16x32_bf16 v[62:65], v[94:97], v[90:93], v[62:65]
	v_mfma_f32_16x16x32_bf16 v[30:33], v[98:101], v[90:93], v[30:33]
	ds_read_b128 v[86:89], v14 offset:4096
	ds_read_b128 v[90:93], v14 offset:6144
	s_waitcnt vmcnt(0)
	s_waitcnt lgkmcnt(0)
	v_mfma_f32_16x16x32_bf16 v[74:77], v[70:73], v[86:89], v[74:77]
	s_barrier
	v_mfma_f32_16x16x32_bf16 v[78:81], v[82:85], v[86:89], v[78:81]
	v_mfma_f32_16x16x32_bf16 v[8:11], v[94:97], v[86:89], v[8:11]
	v_mfma_f32_16x16x32_bf16 v[66:69], v[98:101], v[86:89], v[66:69]
	ds_read_b128 v[86:89], v16 offset:51200
	v_mfma_f32_16x16x32_bf16 v[18:21], v[70:73], v[90:93], v[18:21]
	ds_read_b128 v[70:73], v16 offset:49152
	v_mfma_f32_16x16x32_bf16 v[22:25], v[82:85], v[90:93], v[22:25]
	ds_read_b128 v[82:85], v13 offset:32768
	v_mfma_f32_16x16x32_bf16 v[38:41], v[94:97], v[90:93], v[38:41]
	ds_read_b128 v[94:97], v16 offset:55296
	v_mfma_f32_16x16x32_bf16 v[46:49], v[98:101], v[90:93], v[46:49]
	ds_read_b128 v[90:93], v16 offset:53248
	v_or_b32_e32 v98, 16, v6
	v_or_b32_e32 v100, 32, v6
	s_waitcnt lgkmcnt(2)
	v_mfma_f32_16x16x32_bf16 v[34:37], v[70:73], v[82:85], v[34:37]
	v_ashrrev_i32_e32 v99, 31, v98
	v_ashrrev_i32_e32 v101, 31, v100
	v_mfma_f32_16x16x32_bf16 v[42:45], v[86:89], v[82:85], v[42:45]
	s_waitcnt lgkmcnt(0)
	v_mfma_f32_16x16x32_bf16 v[50:53], v[90:93], v[82:85], v[50:53]
	v_mfma_f32_16x16x32_bf16 v[26:29], v[94:97], v[82:85], v[26:29]
	ds_read_b128 v[82:85], v13 offset:34816
	s_waitcnt lgkmcnt(0)
	v_mfma_f32_16x16x32_bf16 v[54:57], v[70:73], v[82:85], v[54:57]
	v_mfma_f32_16x16x32_bf16 v[58:61], v[86:89], v[82:85], v[58:61]
	v_mfma_f32_16x16x32_bf16 v[62:65], v[90:93], v[82:85], v[62:65]
	v_mfma_f32_16x16x32_bf16 v[30:33], v[94:97], v[82:85], v[30:33]
	ds_read_b128 v[82:85], v13 offset:36864
	s_waitcnt lgkmcnt(0)
; template <int WT, class Epi>
; DEV void gemm_tile(const bf16_t* __restrict__ A, int lda, const bf16_t* __restrict__ Bt, int ldb, int K, unsigned char* lds, const Epi& epi) {
;     ...
;     for (int kt = 0; kt < nk; ++kt) {
;         if (NSTG == 4 && kt + 2 < nk) { if (FI == 2) asm volatile("s_waitcnt vmcnt(8)" ::: "memory"); else asm volatile("s_waitcnt vmcnt(0)" ::: "memory"); }
;         else asm volatile("s_waitcnt vmcnt(0)" ::: "memory");
;         __syncthreads();
;         if (kt + NSTG - 1 < nk) GLDS_STAGE(nxt, kt + NSTG - 1);
; #pragma unroll
;         for (int kh = 0; kh < 2; ++kh) {
;             bf16x8 af[FI], bfr[FI];
;             const int ch = ((kh * 4 + fq) ^ sw) << 4;
; #pragma unroll
;             for (int i = 0; i < FI; ++i) { af[i] = *(const bf16x8*)(lds + cur + aoff + i * 2048 + ch); bfr[i] = *(const bf16x8*)(lds + cur + boff + i * 2048 + ch); }
; #pragma unroll
;             for (int mi = 0; mi < FI; ++mi)
; #pragma unroll
;                 for (int ni = 0; ni < FI; ++ni) acc[mi][ni] = __builtin_amdgcn_mfma_f32_16x16x32_bf16(bfr[ni], af[mi], acc[mi][ni], 0, 0, 0);
;         }
;         nxt = cur; cur += STB; if (cur == NSTG * STB) cur = 0;
;     }
;     ...
;     __syncthreads();
;     if constexpr (Epi::STAGE) {
;         constexpr int RB = 4 * WT, CPR = RB / 16;
; #pragma unroll
;         for (int mi = 0; mi < FI; ++mi)
; #pragma unroll
;             for (int ni = 0; ni < FI; ++ni) {
;                 const int row = wr * WT + mi * 16 + fr, col = wc * WT + ni * 16 + fq * 4;
;                 const f32x4 v = epi.xform(row, col, acc[mi][ni]);
;                 uint2 w; w.x = cvt_pk_bf16(v[0], v[1]); w.y = cvt_pk_bf16(v[2], v[3]);
;                 *(uint2*)(lds + row * RB + ((((col >> 3) ^ (row & (CPR - 1))) << 4) | (((col >> 2) & 1) << 3))) = w;
;             }
;         __syncthreads();
; #pragma unroll
;         for (int i = 0; i < (2 * WT * CPR) / 256; ++i) {
;             const int idx = tid + 256 * i, row = idx / CPR, cp = idx % CPR, c = cp ^ (row & (CPR - 1));
;             const uint4 d = *(const uint4*)(lds + row * RB + (cp << 4));
;             *(uint4*)(epi.obase + (size_t)row * epi.old + c * 8) = epi.finish(row, c * 8, d);
;         }
;         __syncthreads();
;     } else {
; #pragma unroll
;         for (int mi = 0; mi < FI; ++mi)
; #pragma unroll
	v_mfma_f32_16x16x32_bf16 v[74:77], v[70:73], v[82:85], v[74:77]
	v_mfma_f32_16x16x32_bf16 v[78:81], v[86:89], v[82:85], v[78:81]
	v_mfma_f32_16x16x32_bf16 v[8:11], v[90:93], v[82:85], v[8:11]
	v_mfma_f32_16x16x32_bf16 v[66:69], v[94:97], v[82:85], v[66:69]
	ds_read_b128 v[82:85], v13 offset:38912
	v_lshlrev_b32_e32 v13, 2, v7
	v_ashrrev_i32_e32 v7, 31, v6
	s_waitcnt lgkmcnt(0)
	v_mfma_f32_16x16x32_bf16 v[16:19], v[70:73], v[82:85], v[18:21]
	ds_read_b128 v[70:73], v15 offset:49152
	v_lshlrev_b64 v[106:107], 12, v[6:7]
	v_lshl_add_u64 v[6:7], v[104:105], 0, s[4:5]
	v_mfma_f32_16x16x32_bf16 v[20:23], v[86:89], v[82:85], v[22:25]
	ds_read_b128 v[86:89], v15 offset:51200
	v_lshl_or_b32 v4, v4, 4, v13
	v_mfma_f32_16x16x32_bf16 v[38:41], v[90:93], v[82:85], v[38:41]
	ds_read_b128 v[90:93], v15 offset:53248
	v_mfma_f32_16x16x32_bf16 v[46:49], v[94:97], v[82:85], v[46:49]
	ds_read_b128 v[94:97], v15 offset:55296
	ds_read_b128 v[82:85], v14 offset:32768
	s_waitcnt lgkmcnt(0)
	v_mfma_f32_16x16x32_bf16 v[34:37], v[70:73], v[82:85], v[34:37]
	v_mfma_f32_16x16x32_bf16 v[42:45], v[86:89], v[82:85], v[42:45]
	s_nop 6
	v_mul_f32_e64 v36, v36, s74
	v_mul_f32_e64 v37, v37, s74
	v_pk_mul_f32 v[34:35], v[34:35], s[74:75] op_sel_hi:[1,0]
	v_mfma_f32_16x16x32_bf16 v[50:53], v[90:93], v[82:85], v[50:53]
	v_mfma_f32_16x16x32_bf16 v[24:27], v[94:97], v[82:85], v[26:29]
	ds_read_b128 v[82:85], v14 offset:34816
	v_pk_mul_f32 v[44:45], v[44:45], s[74:75] op_sel_hi:[1,0]
	v_pk_mul_f32 v[42:43], v[42:43], s[74:75] op_sel_hi:[1,0]
	s_waitcnt lgkmcnt(0)
	v_mfma_f32_16x16x32_bf16 v[54:57], v[70:73], v[82:85], v[54:57]
	s_nop 1
	v_mul_f32_e64 v52, v52, s74
	v_mul_f32_e64 v53, v53, s74
	v_pk_mul_f32 v[50:51], v[50:51], s[74:75] op_sel_hi:[1,0]
	v_pk_mul_f32 v[26:27], v[26:27], s[74:75] op_sel_hi:[1,0]
	v_mfma_f32_16x16x32_bf16 v[58:61], v[86:89], v[82:85], v[58:61]
	v_mul_f32_e64 v24, v24, s74
	v_mul_f32_e64 v25, v25, s74
	v_pk_mul_f32 v[56:57], v[56:57], s[74:75] op_sel_hi:[1,0]
	v_pk_mul_f32 v[54:55], v[54:55], s[74:75] op_sel_hi:[1,0]
	v_mfma_f32_16x16x32_bf16 v[62:65], v[90:93], v[82:85], v[62:65]
	v_mfma_f32_16x16x32_bf16 v[28:31], v[94:97], v[82:85], v[30:33]
	ds_read_b128 v[82:85], v14 offset:36864
	s_nop 0
	v_pk_mul_f32 v[60:61], v[60:61], s[74:75] op_sel_hi:[1,0]
	v_pk_mul_f32 v[58:59], v[58:59], s[74:75] op_sel_hi:[1,0]
	s_waitcnt lgkmcnt(0)
	v_mfma_f32_16x16x32_bf16 v[74:77], v[70:73], v[82:85], v[74:77]
	v_lshlrev_b64 v[32:33], 12, v[98:99]
	v_lshlrev_b64 v[98:99], 12, v[100:101]
	v_lshlrev_b64 v[100:101], 12, v[102:103]
	v_mfma_f32_16x16x32_bf16 v[78:81], v[86:89], v[82:85], v[78:81]
	v_lshl_add_u64 v[102:103], v[6:7], 0, s[78:79]
	v_lshl_add_u64 v[32:33], v[102:103], 0, v[32:33]
	v_pk_mul_f32 v[64:65], v[64:65], s[74:75] op_sel_hi:[1,0]
	v_mfma_f32_16x16x32_bf16 v[6:9], v[90:93], v[82:85], v[8:11]
	v_mul_f32_e64 v62, v62, s74
	v_mul_f32_e64 v63, v63, s74
	v_pk_mul_f32 v[30:31], v[30:31], s[74:75] op_sel_hi:[1,0]
	v_pk_mul_f32 v[28:29], v[28:29], s[74:75] op_sel_hi:[1,0]
	v_mfma_f32_16x16x32_bf16 v[66:69], v[94:97], v[82:85], v[66:69]
	ds_read_b128 v[82:85], v14 offset:38912
	v_lshl_add_u64 v[10:11], v[102:103], 0, v[106:107]
	v_lshl_add_u64 v[10:11], v[10:11], 0, v[4:5]
	s_waitcnt lgkmcnt(0)
	v_mfma_f32_16x16x32_bf16 v[14:17], v[70:73], v[82:85], v[16:19]
	v_lshl_add_u64 v[70:71], v[102:103], 0, v[98:99]
	v_lshl_add_u64 v[72:73], v[102:103], 0, v[100:101]
	v_mfma_f32_16x16x32_bf16 v[18:21], v[86:89], v[82:85], v[20:23]
	v_lshl_add_u64 v[86:87], v[72:73], 0, v[4:5]
	s_barrier
	v_mfma_f32_16x16x32_bf16 v[38:41], v[90:93], v[82:85], v[38:41]
	v_lshl_add_u64 v[22:23], v[32:33], 0, v[4:5]
	v_lshl_add_u64 v[32:33], v[70:71], 0, v[4:5]
	v_pk_mul_f32 v[72:73], v[76:77], s[74:75] op_sel_hi:[1,0]
	v_mfma_f32_16x16x32_bf16 v[46:49], v[94:97], v[82:85], v[46:49]
	v_mul_f32_e64 v70, v74, s74
	v_mul_f32_e64 v71, v75, s74
	v_pk_mul_f32 v[76:77], v[80:81], s[74:75] op_sel_hi:[1,0]
	v_pk_mul_f32 v[74:75], v[78:79], s[74:75] op_sel_hi:[1,0]
	v_pk_mul_f32 v[8:9], v[8:9], s[74:75] op_sel_hi:[1,0]
	v_pk_mul_f32 v[6:7], v[6:7], s[74:75] op_sel_hi:[1,0]
	v_pk_mul_f32 v[68:69], v[68:69], s[74:75] op_sel_hi:[1,0]
	v_pk_mul_f32 v[66:67], v[66:67], s[74:75] op_sel_hi:[1,0]
	v_pk_mul_f32 v[16:17], v[16:17], s[74:75] op_sel_hi:[1,0]
	v_pk_mul_f32 v[14:15], v[14:15], s[74:75] op_sel_hi:[1,0]
	v_pk_mul_f32 v[20:21], v[20:21], s[74:75] op_sel_hi:[1,0]
	v_pk_mul_f32 v[18:19], v[18:19], s[74:75] op_sel_hi:[1,0]
	v_pk_mul_f32 v[40:41], v[40:41], s[74:75] op_sel_hi:[1,0]
	v_pk_mul_f32 v[38:39], v[38:39], s[74:75] op_sel_hi:[1,0]
	v_pk_mul_f32 v[48:49], v[48:49], s[74:75] op_sel_hi:[1,0]
	v_pk_mul_f32 v[46:47], v[46:47], s[74:75] op_sel_hi:[1,0]
	global_store_dwordx4 v[10:11], v[34:37], off
	global_store_dwordx4 v[10:11], v[42:45], off offset:64
	global_store_dwordx4 v[10:11], v[50:53], off offset:128
	global_store_dwordx4 v[10:11], v[24:27], off offset:192
	global_store_dwordx4 v[22:23], v[54:57], off
	global_store_dwordx4 v[22:23], v[58:61], off offset:64
	global_store_dwordx4 v[22:23], v[62:65], off offset:128
	global_store_dwordx4 v[22:23], v[28:31], off offset:192
	global_store_dwordx4 v[32:33], v[70:73], off
	global_store_dwordx4 v[32:33], v[74:77], off offset:64
	global_store_dwordx4 v[32:33], v[6:9], off offset:128
	global_store_dwordx4 v[32:33], v[66:69], off offset:192
	global_store_dwordx4 v[86:87], v[14:17], off
	global_store_dwordx4 v[86:87], v[18:21], off offset:64
	global_store_dwordx4 v[86:87], v[38:41], off offset:128
	global_store_dwordx4 v[86:87], v[46:49], off offset:192
	s_cbranch_scc1 .LBB0_1295
	v_readlane_b32 s94, v252, 0
	v_readlane_b32 s95, v252, 1
	s_cmpk_lg_i32 s33, 0x100
	s_cbranch_scc1 .LBB0_1297
; DEV void store_bf4(bf16_t* p, f32x4 v) { uint2 w; w.x = cvt_pk_bf16(v[0], v[1]); w.y = cvt_pk_bf16(v[2], v[3]); *(uint2*)p = w; }
; #define VLOOP(t, N) for (int t##0_ = 2 * bid, t = min(t##0_ + vb, (N) - 1); t##0_ < (N); t##0_ += VG, t = min(t##0_ + vb, (N) - 1))
; __global__ void __launch_bounds__(512) hymba_fwd(Params p) {
;     ...
;     if (IN_PH(8)) { PH_LOCALS
;         const int NS1 = 16 * 16 * 2;
;         VLOOP(t, NS1) { const int bhd = t >> 5, v = t & 31, mt = v >> 1, nt = v & 1, b = bhd >> 2, hd = bhd & 3;
;     ...
;     if (IN_PH(9)) { PH_LOCALS
;     for (int r = bid * 8 + wid; r < TP * 4; r += G * 8) {
;         const f32x4 v = __builtin_nontemporal_load((const f32x4*)(sc + (size_t)r * 256 + lane * 4));
;         const float mx = wave_max(fmaxf(fmaxf(v[0], v[1]), fmaxf(v[2], v[3])));
;         f32x4 e; e[0] = __expf(v[0] - mx); e[1] = __expf(v[1] - mx); e[2] = __expf(v[2] - mx); e[3] = __expf(v[3] - mx);
;         const float inv = 1.f / wave_sum(e[0] + e[1] + e[2] + e[3]);
;         store_bf4(pb + (size_t)(r >> 2) * LDP + (r & 3) * 256 + lane * 4, e * inv);
	s_waitcnt vmcnt(0)
	s_barrier
	v_mbcnt_lo_u32_b32 v2, -1, 0
	v_mbcnt_hi_u32_b32 v2, -1, v2
	v_lshrrev_b32_e32 v6, 6, v0
	s_lshr_b32 s4, s2, 6
	s_lshl_b32 s4, s4, 11
	s_and_b32 s5, s2, 15
	s_lshl_b32 s5, s5, 7
	s_add_i32 s4, s4, s5
	s_bfe_u32 s5, s2, 0x20004
	v_xor_b32_e32 v8, 32, v2
	v_xor_b32_e32 v9, 16, v2
	v_xor_b32_e32 v10, 8, v2
	v_xor_b32_e32 v11, 4, v2
	v_xor_b32_e32 v12, 2, v2
	v_xor_b32_e32 v13, 1, v2
	v_lshlrev_b32_e32 v8, 2, v8
	v_lshlrev_b32_e32 v9, 2, v9
	v_lshlrev_b32_e32 v10, 2, v10
	v_lshlrev_b32_e32 v11, 2, v11
	v_lshlrev_b32_e32 v12, 2, v12
	v_lshlrev_b32_e32 v13, 2, v13
	v_add_u32_e32 v1, s4, v6
	s_lshl_b32 s6, s5, 10
	v_lshlrev_b32_e32 v14, 12, v1
	v_lshl_add_u32 v15, v2, 4, s6
	v_add_u32_e32 v14, v14, v15
	v_mov_b32_e32 v15, 0
	s_mov_b64 s[6:7], 0x1ef39000
	v_lshl_add_u64 v[4:5], v[158:159], 0, s[6:7]
	v_lshl_add_u64 v[4:5], v[4:5], 0, v[14:15]
	s_mov_b64 s[6:7], 0x20f39000
	v_lshl_add_u64 v[20:21], v[158:159], 0, s[6:7]
	s_movk_i32 s12, 0x880
	v_mad_i64_i32 v[20:21], s[16:17], v1, s12, v[20:21]
	s_lshl_b32 s6, s5, 9
	v_lshl_add_u32 v14, v2, 3, s6
	v_lshl_add_u64 v[20:21], v[20:21], 0, v[14:15]
	s_mov_b64 s[8:9], 0x8000
	s_mov_b64 s[10:11], 0x4400
	global_load_dwordx4 v[24:27], v[4:5], off nt
	v_lshl_add_u64 v[4:5], v[4:5], 0, s[8:9]
	global_load_dwordx4 v[28:31], v[4:5], off nt
	v_lshl_add_u64 v[4:5], v[4:5], 0, s[8:9]
	global_load_dwordx4 v[32:35], v[4:5], off nt
	v_lshl_add_u64 v[4:5], v[4:5], 0, s[8:9]
	global_load_dwordx4 v[36:39], v[4:5], off nt
	v_lshl_add_u64 v[4:5], v[4:5], 0, s[8:9]
	global_load_dwordx4 v[40:43], v[4:5], off nt
	v_lshl_add_u64 v[4:5], v[4:5], 0, s[8:9]
	global_load_dwordx4 v[44:47], v[4:5], off nt
	v_lshl_add_u64 v[4:5], v[4:5], 0, s[8:9]
	global_load_dwordx4 v[48:51], v[4:5], off nt
	v_lshl_add_u64 v[4:5], v[4:5], 0, s[8:9]
	global_load_dwordx4 v[52:55], v[4:5], off nt
	v_lshl_add_u64 v[4:5], v[4:5], 0, s[8:9]
	s_waitcnt vmcnt(4)
	v_max_f32_e32 v56, v27, v27
	v_max_f32_e32 v60, v26, v26
	v_max_f32_e32 v56, v60, v56
	v_max3_f32 v56, v24, v25, v56
	v_max_f32_e32 v57, v31, v31
	v_max_f32_e32 v61, v30, v30
	v_max_f32_e32 v57, v61, v57
	v_max3_f32 v57, v28, v29, v57
	v_max_f32_e32 v58, v35, v35
	v_max_f32_e32 v62, v34, v34
	v_max_f32_e32 v58, v62, v58
	v_max3_f32 v58, v32, v33, v58
	v_max_f32_e32 v59, v39, v39
	v_max_f32_e32 v63, v38, v38
	v_max_f32_e32 v59, v63, v59
	v_max3_f32 v59, v36, v37, v59
	ds_bpermute_b32 v60, v8, v56
	ds_bpermute_b32 v61, v8, v57
	ds_bpermute_b32 v62, v8, v58
	ds_bpermute_b32 v63, v8, v59
	s_waitcnt lgkmcnt(3)
	v_max_f32_e32 v60, v60, v60
	v_max_f32_e32 v56, v56, v60
	s_waitcnt lgkmcnt(2)
	v_max_f32_e32 v61, v61, v61
	v_max_f32_e32 v57, v57, v61
	s_waitcnt lgkmcnt(1)
	v_max_f32_e32 v62, v62, v62
	v_max_f32_e32 v58, v58, v62
	s_waitcnt lgkmcnt(0)
	v_max_f32_e32 v63, v63, v63
	v_max_f32_e32 v59, v59, v63
	ds_bpermute_b32 v60, v9, v56
	ds_bpermute_b32 v61, v9, v57
	ds_bpermute_b32 v62, v9, v58
	ds_bpermute_b32 v63, v9, v59
	s_waitcnt lgkmcnt(3)
	v_max_f32_e32 v60, v60, v60
	v_max_f32_e32 v56, v56, v60
	s_waitcnt lgkmcnt(2)
	v_max_f32_e32 v61, v61, v61
	v_max_f32_e32 v57, v57, v61
	s_waitcnt lgkmcnt(1)
	v_max_f32_e32 v62, v62, v62
	v_max_f32_e32 v58, v58, v62
	s_waitcnt lgkmcnt(0)
	v_max_f32_e32 v63, v63, v63
	v_max_f32_e32 v59, v59, v63
	ds_bpermute_b32 v60, v10, v56
	ds_bpermute_b32 v61, v10, v57
	ds_bpermute_b32 v62, v10, v58
	ds_bpermute_b32 v63, v10, v59
	s_waitcnt lgkmcnt(3)
	v_max_f32_e32 v60, v60, v60
	v_max_f32_e32 v56, v56, v60
	s_waitcnt lgkmcnt(2)
	v_max_f32_e32 v61, v61, v61
	v_max_f32_e32 v57, v57, v61
	s_waitcnt lgkmcnt(1)
	v_max_f32_e32 v62, v62, v62
	v_max_f32_e32 v58, v58, v62
	s_waitcnt lgkmcnt(0)
	v_max_f32_e32 v63, v63, v63
	v_max_f32_e32 v59, v59, v63
	ds_bpermute_b32 v60, v11, v56
	ds_bpermute_b32 v61, v11, v57
	ds_bpermute_b32 v62, v11, v58
	ds_bpermute_b32 v63, v11, v59
	s_waitcnt lgkmcnt(3)
	v_max_f32_e32 v60, v60, v60
	v_max_f32_e32 v56, v56, v60
	s_waitcnt lgkmcnt(2)
	v_max_f32_e32 v61, v61, v61
	v_max_f32_e32 v57, v57, v61
	s_waitcnt lgkmcnt(1)
	v_max_f32_e32 v62, v62, v62
	v_max_f32_e32 v58, v58, v62
	s_waitcnt lgkmcnt(0)
	v_max_f32_e32 v63, v63, v63
	v_max_f32_e32 v59, v59, v63
	ds_bpermute_b32 v60, v12, v56
	ds_bpermute_b32 v61, v12, v57
	ds_bpermute_b32 v62, v12, v58
	ds_bpermute_b32 v63, v12, v59
	s_waitcnt lgkmcnt(3)
	v_max_f32_e32 v60, v60, v60
	v_max_f32_e32 v56, v56, v60
	s_waitcnt lgkmcnt(2)
	v_max_f32_e32 v61, v61, v61
	v_max_f32_e32 v57, v57, v61
	s_waitcnt lgkmcnt(1)
	v_max_f32_e32 v62, v62, v62
	v_max_f32_e32 v58, v58, v62
	s_waitcnt lgkmcnt(0)
	v_max_f32_e32 v63, v63, v63
	v_max_f32_e32 v59, v59, v63
	ds_bpermute_b32 v60, v13, v56
	ds_bpermute_b32 v61, v13, v57
	ds_bpermute_b32 v62, v13, v58
	ds_bpermute_b32 v63, v13, v59
	s_waitcnt lgkmcnt(3)
	v_max_f32_e32 v60, v60, v60
	v_max_f32_e32 v56, v56, v60
	s_waitcnt lgkmcnt(2)
	v_max_f32_e32 v61, v61, v61
	v_max_f32_e32 v57, v57, v61
	s_waitcnt lgkmcnt(1)
	v_max_f32_e32 v62, v62, v62
	v_max_f32_e32 v58, v58, v62
	s_waitcnt lgkmcnt(0)
; DEV void store_bf4(bf16_t* p, f32x4 v) { uint2 w; w.x = cvt_pk_bf16(v[0], v[1]); w.y = cvt_pk_bf16(v[2], v[3]); *(uint2*)p = w; }
; DEV float wave_sum(float v) {
; #pragma unroll
;     for (int o = 32; o >= 1; o >>= 1) v += __shfl_xor(v, o);
;     return v;
; }
; DEV float wave_max(float v) {
; #pragma unroll
;     for (int o = 32; o >= 1; o >>= 1) v = fmaxf(v, __shfl_xor(v, o));
;     return v;
; }
; __global__ void __launch_bounds__(512) hymba_fwd(Params p) {
;     ...
;     for (int r = bid * 8 + wid; r < TP * 4; r += G * 8) {
;         const f32x4 v = __builtin_nontemporal_load((const f32x4*)(sc + (size_t)r * 256 + lane * 4));
;         const float mx = wave_max(fmaxf(fmaxf(v[0], v[1]), fmaxf(v[2], v[3])));
;         f32x4 e; e[0] = __expf(v[0] - mx); e[1] = __expf(v[1] - mx); e[2] = __expf(v[2] - mx); e[3] = __expf(v[3] - mx);
;         const float inv = 1.f / wave_sum(e[0] + e[1] + e[2] + e[3]);
;         store_bf4(pb + (size_t)(r >> 2) * LDP + (r & 3) * 256 + lane * 4, e * inv);
	v_max_f32_e32 v63, v63, v63
	v_max_f32_e32 v59, v59, v63
	v_sub_f32_e32 v24, v24, v56
	v_sub_f32_e32 v25, v25, v56
	v_sub_f32_e32 v26, v26, v56
	v_sub_f32_e32 v27, v27, v56
	v_mul_f32_e32 v24, 0x3fb8aa3b, v24
	v_mul_f32_e32 v25, 0x3fb8aa3b, v25
	v_mul_f32_e32 v26, 0x3fb8aa3b, v26
	v_mul_f32_e32 v27, 0x3fb8aa3b, v27
	v_sub_f32_e32 v28, v28, v57
	v_sub_f32_e32 v29, v29, v57
	v_sub_f32_e32 v30, v30, v57
	v_sub_f32_e32 v31, v31, v57
	v_mul_f32_e32 v28, 0x3fb8aa3b, v28
	v_mul_f32_e32 v29, 0x3fb8aa3b, v29
	v_mul_f32_e32 v30, 0x3fb8aa3b, v30
	v_mul_f32_e32 v31, 0x3fb8aa3b, v31
	v_sub_f32_e32 v32, v32, v58
	v_sub_f32_e32 v33, v33, v58
	v_sub_f32_e32 v34, v34, v58
	v_sub_f32_e32 v35, v35, v58
	v_mul_f32_e32 v32, 0x3fb8aa3b, v32
	v_mul_f32_e32 v33, 0x3fb8aa3b, v33
	v_mul_f32_e32 v34, 0x3fb8aa3b, v34
	v_mul_f32_e32 v35, 0x3fb8aa3b, v35
	v_sub_f32_e32 v36, v36, v59
	v_sub_f32_e32 v37, v37, v59
	v_sub_f32_e32 v38, v38, v59
	v_sub_f32_e32 v39, v39, v59
	v_mul_f32_e32 v36, 0x3fb8aa3b, v36
	v_mul_f32_e32 v37, 0x3fb8aa3b, v37
	v_mul_f32_e32 v38, 0x3fb8aa3b, v38
	v_mul_f32_e32 v39, 0x3fb8aa3b, v39
	v_exp_f32_e32 v24, v24
	v_exp_f32_e32 v25, v25
	v_exp_f32_e32 v26, v26
	v_exp_f32_e32 v27, v27
	v_exp_f32_e32 v28, v28
	v_exp_f32_e32 v29, v29
	v_exp_f32_e32 v30, v30
	v_exp_f32_e32 v31, v31
	v_exp_f32_e32 v32, v32
	v_exp_f32_e32 v33, v33
	v_exp_f32_e32 v34, v34
	v_exp_f32_e32 v35, v35
	v_exp_f32_e32 v36, v36
	v_exp_f32_e32 v37, v37
	v_exp_f32_e32 v38, v38
	v_exp_f32_e32 v39, v39
	v_add_f32_e32 v56, v24, v25
	v_add_f32_e32 v56, v26, v56
	v_add_f32_e32 v56, v27, v56
	v_add_f32_e32 v57, v28, v29
	v_add_f32_e32 v57, v30, v57
	v_add_f32_e32 v57, v31, v57
	v_add_f32_e32 v58, v32, v33
	v_add_f32_e32 v58, v34, v58
	v_add_f32_e32 v58, v35, v58
	v_add_f32_e32 v59, v36, v37
	v_add_f32_e32 v59, v38, v59
	v_add_f32_e32 v59, v39, v59
	ds_bpermute_b32 v60, v8, v56
	ds_bpermute_b32 v61, v8, v57
	ds_bpermute_b32 v62, v8, v58
	ds_bpermute_b32 v63, v8, v59
	s_waitcnt lgkmcnt(3)
	v_add_f32_e32 v56, v56, v60
	s_waitcnt lgkmcnt(2)
	v_add_f32_e32 v57, v57, v61
	s_waitcnt lgkmcnt(1)
	v_add_f32_e32 v58, v58, v62
	s_waitcnt lgkmcnt(0)
	v_add_f32_e32 v59, v59, v63
	ds_bpermute_b32 v60, v9, v56
	ds_bpermute_b32 v61, v9, v57
	ds_bpermute_b32 v62, v9, v58
	ds_bpermute_b32 v63, v9, v59
	s_waitcnt lgkmcnt(3)
	v_add_f32_e32 v56, v56, v60
	s_waitcnt lgkmcnt(2)
	v_add_f32_e32 v57, v57, v61
	s_waitcnt lgkmcnt(1)
	v_add_f32_e32 v58, v58, v62
	s_waitcnt lgkmcnt(0)
	v_add_f32_e32 v59, v59, v63
	ds_bpermute_b32 v60, v10, v56
	ds_bpermute_b32 v61, v10, v57
	ds_bpermute_b32 v62, v10, v58
	ds_bpermute_b32 v63, v10, v59
	s_waitcnt lgkmcnt(3)
	v_add_f32_e32 v56, v56, v60
	s_waitcnt lgkmcnt(2)
	v_add_f32_e32 v57, v57, v61
	s_waitcnt lgkmcnt(1)
	v_add_f32_e32 v58, v58, v62
	s_waitcnt lgkmcnt(0)
	v_add_f32_e32 v59, v59, v63
	ds_bpermute_b32 v60, v11, v56
	ds_bpermute_b32 v61, v11, v57
	ds_bpermute_b32 v62, v11, v58
	ds_bpermute_b32 v63, v11, v59
	s_waitcnt lgkmcnt(3)
	v_add_f32_e32 v56, v56, v60
	s_waitcnt lgkmcnt(2)
	v_add_f32_e32 v57, v57, v61
	s_waitcnt lgkmcnt(1)
	v_add_f32_e32 v58, v58, v62
	s_waitcnt lgkmcnt(0)
	v_add_f32_e32 v59, v59, v63
	ds_bpermute_b32 v60, v12, v56
	ds_bpermute_b32 v61, v12, v57
	ds_bpermute_b32 v62, v12, v58
	ds_bpermute_b32 v63, v12, v59
	s_waitcnt lgkmcnt(3)
	v_add_f32_e32 v56, v56, v60
	s_waitcnt lgkmcnt(2)
	v_add_f32_e32 v57, v57, v61
	s_waitcnt lgkmcnt(1)
	v_add_f32_e32 v58, v58, v62
	s_waitcnt lgkmcnt(0)
	v_add_f32_e32 v59, v59, v63
	ds_bpermute_b32 v60, v13, v56
	ds_bpermute_b32 v61, v13, v57
	ds_bpermute_b32 v62, v13, v58
	ds_bpermute_b32 v63, v13, v59
	s_waitcnt lgkmcnt(3)
	v_add_f32_e32 v56, v56, v60
	s_waitcnt lgkmcnt(2)
	v_add_f32_e32 v57, v57, v61
	s_waitcnt lgkmcnt(1)
	v_add_f32_e32 v58, v58, v62
	s_waitcnt lgkmcnt(0)
	v_add_f32_e32 v59, v59, v63
	v_div_scale_f32 v64, s[16:17], v56, v56, 1.0
	v_rcp_f32_e32 v65, v64
	v_div_scale_f32 v66, vcc, 1.0, v56, 1.0
	v_fma_f32 v67, -v64, v65, 1.0
	v_fmac_f32_e32 v65, v67, v65
	v_mul_f32_e32 v67, v66, v65
	v_fma_f32 v68, -v64, v67, v66
	v_fmac_f32_e32 v67, v68, v65
	v_fma_f32 v64, -v64, v67, v66
	v_div_fmas_f32 v64, v64, v65, v67
	v_div_fixup_f32 v56, v64, v56, 1.0
	v_mul_f32_e32 v24, v24, v56
	v_mul_f32_e32 v25, v25, v56
	v_mul_f32_e32 v26, v26, v56
	v_mul_f32_e32 v27, v27, v56
	v_cvt_pk_bf16_f32 v24, v24, v25
	v_cvt_pk_bf16_f32 v25, v26, v27
	global_store_dwordx2 v[20:21], v[24:25], off
	v_lshl_add_u64 v[20:21], v[20:21], 0, s[10:11]
	v_div_scale_f32 v64, s[16:17], v57, v57, 1.0
	v_rcp_f32_e32 v65, v64
	v_div_scale_f32 v66, vcc, 1.0, v57, 1.0
	v_fma_f32 v67, -v64, v65, 1.0
	v_fmac_f32_e32 v65, v67, v65
	v_mul_f32_e32 v67, v66, v65
	v_fma_f32 v68, -v64, v67, v66
	v_fmac_f32_e32 v67, v68, v65
	v_fma_f32 v64, -v64, v67, v66
	v_div_fmas_f32 v64, v64, v65, v67
	v_div_fixup_f32 v57, v64, v57, 1.0
	v_mul_f32_e32 v28, v28, v57
	v_mul_f32_e32 v29, v29, v57
	v_mul_f32_e32 v30, v30, v57
	v_mul_f32_e32 v31, v31, v57
	v_cvt_pk_bf16_f32 v28, v28, v29
	v_cvt_pk_bf16_f32 v29, v30, v31
	global_store_dwordx2 v[20:21], v[28:29], off
	v_lshl_add_u64 v[20:21], v[20:21], 0, s[10:11]
	v_div_scale_f32 v64, s[16:17], v58, v58, 1.0
	v_rcp_f32_e32 v65, v64
	v_div_scale_f32 v66, vcc, 1.0, v58, 1.0
	v_fma_f32 v67, -v64, v65, 1.0
	v_fmac_f32_e32 v65, v67, v65
	v_mul_f32_e32 v67, v66, v65
	v_fma_f32 v68, -v64, v67, v66
	v_fmac_f32_e32 v67, v68, v65
	v_fma_f32 v64, -v64, v67, v66
	v_div_fmas_f32 v64, v64, v65, v67
	v_div_fixup_f32 v58, v64, v58, 1.0
	v_mul_f32_e32 v32, v32, v58
	v_mul_f32_e32 v33, v33, v58
	v_mul_f32_e32 v34, v34, v58
	v_mul_f32_e32 v35, v35, v58
	v_cvt_pk_bf16_f32 v32, v32, v33
	v_cvt_pk_bf16_f32 v33, v34, v35
	global_store_dwordx2 v[20:21], v[32:33], off
	v_lshl_add_u64 v[20:21], v[20:21], 0, s[10:11]
	v_div_scale_f32 v64, s[16:17], v59, v59, 1.0
	v_rcp_f32_e32 v65, v64
	v_div_scale_f32 v66, vcc, 1.0, v59, 1.0
	v_fma_f32 v67, -v64, v65, 1.0
	v_fmac_f32_e32 v65, v67, v65
	v_mul_f32_e32 v67, v66, v65
	v_fma_f32 v68, -v64, v67, v66
	v_fmac_f32_e32 v67, v68, v65
	v_fma_f32 v64, -v64, v67, v66
	v_div_fmas_f32 v64, v64, v65, v67
	v_div_fixup_f32 v59, v64, v59, 1.0
	v_mul_f32_e32 v36, v36, v59
	v_mul_f32_e32 v37, v37, v59
	v_mul_f32_e32 v38, v38, v59
	v_mul_f32_e32 v39, v39, v59
	v_cvt_pk_bf16_f32 v36, v36, v37
	v_cvt_pk_bf16_f32 v37, v38, v39
	global_store_dwordx2 v[20:21], v[36:37], off
	v_lshl_add_u64 v[20:21], v[20:21], 0, s[10:11]
	global_load_dwordx4 v[24:27], v[4:5], off nt
	v_lshl_add_u64 v[4:5], v[4:5], 0, s[8:9]
	global_load_dwordx4 v[28:31], v[4:5], off nt
	v_lshl_add_u64 v[4:5], v[4:5], 0, s[8:9]
	global_load_dwordx4 v[32:35], v[4:5], off nt
	v_lshl_add_u64 v[4:5], v[4:5], 0, s[8:9]
	global_load_dwordx4 v[36:39], v[4:5], off nt
	v_lshl_add_u64 v[4:5], v[4:5], 0, s[8:9]
	s_waitcnt vmcnt(8)
; DEV void store_bf4(bf16_t* p, f32x4 v) { uint2 w; w.x = cvt_pk_bf16(v[0], v[1]); w.y = cvt_pk_bf16(v[2], v[3]); *(uint2*)p = w; }
; DEV float wave_sum(float v) {
; #pragma unroll
;     for (int o = 32; o >= 1; o >>= 1) v += __shfl_xor(v, o);
;     return v;
; }
; DEV float wave_max(float v) {
; #pragma unroll
;     for (int o = 32; o >= 1; o >>= 1) v = fmaxf(v, __shfl_xor(v, o));
;     return v;
; }
; __global__ void __launch_bounds__(512) hymba_fwd(Params p) {
;     ...
;     for (int r = bid * 8 + wid; r < TP * 4; r += G * 8) {
;         const f32x4 v = __builtin_nontemporal_load((const f32x4*)(sc + (size_t)r * 256 + lane * 4));
;         const float mx = wave_max(fmaxf(fmaxf(v[0], v[1]), fmaxf(v[2], v[3])));
;         f32x4 e; e[0] = __expf(v[0] - mx); e[1] = __expf(v[1] - mx); e[2] = __expf(v[2] - mx); e[3] = __expf(v[3] - mx);
;         const float inv = 1.f / wave_sum(e[0] + e[1] + e[2] + e[3]);
;         store_bf4(pb + (size_t)(r >> 2) * LDP + (r & 3) * 256 + lane * 4, e * inv);
	v_max_f32_e32 v56, v43, v43
	v_max_f32_e32 v60, v42, v42
	v_max_f32_e32 v56, v60, v56
	v_max3_f32 v56, v40, v41, v56
	v_max_f32_e32 v57, v47, v47
	v_max_f32_e32 v61, v46, v46
	v_max_f32_e32 v57, v61, v57
	v_max3_f32 v57, v44, v45, v57
	v_max_f32_e32 v58, v51, v51
	v_max_f32_e32 v62, v50, v50
	v_max_f32_e32 v58, v62, v58
	v_max3_f32 v58, v48, v49, v58
	v_max_f32_e32 v59, v55, v55
	v_max_f32_e32 v63, v54, v54
	v_max_f32_e32 v59, v63, v59
	v_max3_f32 v59, v52, v53, v59
	ds_bpermute_b32 v60, v8, v56
	ds_bpermute_b32 v61, v8, v57
	ds_bpermute_b32 v62, v8, v58
	ds_bpermute_b32 v63, v8, v59
	s_waitcnt lgkmcnt(3)
	v_max_f32_e32 v60, v60, v60
	v_max_f32_e32 v56, v56, v60
	s_waitcnt lgkmcnt(2)
	v_max_f32_e32 v61, v61, v61
	v_max_f32_e32 v57, v57, v61
	s_waitcnt lgkmcnt(1)
	v_max_f32_e32 v62, v62, v62
	v_max_f32_e32 v58, v58, v62
	s_waitcnt lgkmcnt(0)
	v_max_f32_e32 v63, v63, v63
	v_max_f32_e32 v59, v59, v63
	ds_bpermute_b32 v60, v9, v56
	ds_bpermute_b32 v61, v9, v57
	ds_bpermute_b32 v62, v9, v58
	ds_bpermute_b32 v63, v9, v59
	s_waitcnt lgkmcnt(3)
	v_max_f32_e32 v60, v60, v60
	v_max_f32_e32 v56, v56, v60
	s_waitcnt lgkmcnt(2)
	v_max_f32_e32 v61, v61, v61
	v_max_f32_e32 v57, v57, v61
	s_waitcnt lgkmcnt(1)
	v_max_f32_e32 v62, v62, v62
	v_max_f32_e32 v58, v58, v62
	s_waitcnt lgkmcnt(0)
	v_max_f32_e32 v63, v63, v63
	v_max_f32_e32 v59, v59, v63
	ds_bpermute_b32 v60, v10, v56
	ds_bpermute_b32 v61, v10, v57
	ds_bpermute_b32 v62, v10, v58
	ds_bpermute_b32 v63, v10, v59
	s_waitcnt lgkmcnt(3)
	v_max_f32_e32 v60, v60, v60
	v_max_f32_e32 v56, v56, v60
	s_waitcnt lgkmcnt(2)
	v_max_f32_e32 v61, v61, v61
	v_max_f32_e32 v57, v57, v61
	s_waitcnt lgkmcnt(1)
	v_max_f32_e32 v62, v62, v62
	v_max_f32_e32 v58, v58, v62
	s_waitcnt lgkmcnt(0)
	v_max_f32_e32 v63, v63, v63
	v_max_f32_e32 v59, v59, v63
	ds_bpermute_b32 v60, v11, v56
	ds_bpermute_b32 v61, v11, v57
	ds_bpermute_b32 v62, v11, v58
	ds_bpermute_b32 v63, v11, v59
	s_waitcnt lgkmcnt(3)
	v_max_f32_e32 v60, v60, v60
	v_max_f32_e32 v56, v56, v60
	s_waitcnt lgkmcnt(2)
	v_max_f32_e32 v61, v61, v61
	v_max_f32_e32 v57, v57, v61
	s_waitcnt lgkmcnt(1)
	v_max_f32_e32 v62, v62, v62
	v_max_f32_e32 v58, v58, v62
	s_waitcnt lgkmcnt(0)
	v_max_f32_e32 v63, v63, v63
	v_max_f32_e32 v59, v59, v63
	ds_bpermute_b32 v60, v12, v56
	ds_bpermute_b32 v61, v12, v57
	ds_bpermute_b32 v62, v12, v58
	ds_bpermute_b32 v63, v12, v59
	s_waitcnt lgkmcnt(3)
	v_max_f32_e32 v60, v60, v60
	v_max_f32_e32 v56, v56, v60
	s_waitcnt lgkmcnt(2)
	v_max_f32_e32 v61, v61, v61
	v_max_f32_e32 v57, v57, v61
	s_waitcnt lgkmcnt(1)
	v_max_f32_e32 v62, v62, v62
	v_max_f32_e32 v58, v58, v62
	s_waitcnt lgkmcnt(0)
	v_max_f32_e32 v63, v63, v63
	v_max_f32_e32 v59, v59, v63
	ds_bpermute_b32 v60, v13, v56
	ds_bpermute_b32 v61, v13, v57
	ds_bpermute_b32 v62, v13, v58
	ds_bpermute_b32 v63, v13, v59
	s_waitcnt lgkmcnt(3)
	v_max_f32_e32 v60, v60, v60
	v_max_f32_e32 v56, v56, v60
	s_waitcnt lgkmcnt(2)
	v_max_f32_e32 v61, v61, v61
	v_max_f32_e32 v57, v57, v61
	s_waitcnt lgkmcnt(1)
	v_max_f32_e32 v62, v62, v62
	v_max_f32_e32 v58, v58, v62
	s_waitcnt lgkmcnt(0)
	v_max_f32_e32 v63, v63, v63
	v_max_f32_e32 v59, v59, v63
	v_sub_f32_e32 v40, v40, v56
	v_sub_f32_e32 v41, v41, v56
	v_sub_f32_e32 v42, v42, v56
	v_sub_f32_e32 v43, v43, v56
	v_mul_f32_e32 v40, 0x3fb8aa3b, v40
	v_mul_f32_e32 v41, 0x3fb8aa3b, v41
	v_mul_f32_e32 v42, 0x3fb8aa3b, v42
	v_mul_f32_e32 v43, 0x3fb8aa3b, v43
	v_sub_f32_e32 v44, v44, v57
	v_sub_f32_e32 v45, v45, v57
	v_sub_f32_e32 v46, v46, v57
	v_sub_f32_e32 v47, v47, v57
	v_mul_f32_e32 v44, 0x3fb8aa3b, v44
	v_mul_f32_e32 v45, 0x3fb8aa3b, v45
	v_mul_f32_e32 v46, 0x3fb8aa3b, v46
	v_mul_f32_e32 v47, 0x3fb8aa3b, v47
	v_sub_f32_e32 v48, v48, v58
	v_sub_f32_e32 v49, v49, v58
	v_sub_f32_e32 v50, v50, v58
	v_sub_f32_e32 v51, v51, v58
	v_mul_f32_e32 v48, 0x3fb8aa3b, v48
	v_mul_f32_e32 v49, 0x3fb8aa3b, v49
	v_mul_f32_e32 v50, 0x3fb8aa3b, v50
	v_mul_f32_e32 v51, 0x3fb8aa3b, v51
	v_sub_f32_e32 v52, v52, v59
	v_sub_f32_e32 v53, v53, v59
	v_sub_f32_e32 v54, v54, v59
	v_sub_f32_e32 v55, v55, v59
	v_mul_f32_e32 v52, 0x3fb8aa3b, v52
	v_mul_f32_e32 v53, 0x3fb8aa3b, v53
	v_mul_f32_e32 v54, 0x3fb8aa3b, v54
	v_mul_f32_e32 v55, 0x3fb8aa3b, v55
	v_exp_f32_e32 v40, v40
	v_exp_f32_e32 v41, v41
	v_exp_f32_e32 v42, v42
	v_exp_f32_e32 v43, v43
	v_exp_f32_e32 v44, v44
	v_exp_f32_e32 v45, v45
	v_exp_f32_e32 v46, v46
	v_exp_f32_e32 v47, v47
	v_exp_f32_e32 v48, v48
	v_exp_f32_e32 v49, v49
	v_exp_f32_e32 v50, v50
	v_exp_f32_e32 v51, v51
	v_exp_f32_e32 v52, v52
	v_exp_f32_e32 v53, v53
	v_exp_f32_e32 v54, v54
	v_exp_f32_e32 v55, v55
	v_add_f32_e32 v56, v40, v41
	v_add_f32_e32 v56, v42, v56
	v_add_f32_e32 v56, v43, v56
	v_add_f32_e32 v57, v44, v45
	v_add_f32_e32 v57, v46, v57
	v_add_f32_e32 v57, v47, v57
	v_add_f32_e32 v58, v48, v49
	v_add_f32_e32 v58, v50, v58
	v_add_f32_e32 v58, v51, v58
	v_add_f32_e32 v59, v52, v53
	v_add_f32_e32 v59, v54, v59
	v_add_f32_e32 v59, v55, v59
	ds_bpermute_b32 v60, v8, v56
	ds_bpermute_b32 v61, v8, v57
	ds_bpermute_b32 v62, v8, v58
	ds_bpermute_b32 v63, v8, v59
	s_waitcnt lgkmcnt(3)
	v_add_f32_e32 v56, v56, v60
	s_waitcnt lgkmcnt(2)
	v_add_f32_e32 v57, v57, v61
	s_waitcnt lgkmcnt(1)
	v_add_f32_e32 v58, v58, v62
	s_waitcnt lgkmcnt(0)
	v_add_f32_e32 v59, v59, v63
	ds_bpermute_b32 v60, v9, v56
	ds_bpermute_b32 v61, v9, v57
	ds_bpermute_b32 v62, v9, v58
	ds_bpermute_b32 v63, v9, v59
	s_waitcnt lgkmcnt(3)
	v_add_f32_e32 v56, v56, v60
	s_waitcnt lgkmcnt(2)
	v_add_f32_e32 v57, v57, v61
	s_waitcnt lgkmcnt(1)
	v_add_f32_e32 v58, v58, v62
	s_waitcnt lgkmcnt(0)
	v_add_f32_e32 v59, v59, v63
	ds_bpermute_b32 v60, v10, v56
	ds_bpermute_b32 v61, v10, v57
	ds_bpermute_b32 v62, v10, v58
	ds_bpermute_b32 v63, v10, v59
	s_waitcnt lgkmcnt(3)
; DEV void store_bf4(bf16_t* p, f32x4 v) { uint2 w; w.x = cvt_pk_bf16(v[0], v[1]); w.y = cvt_pk_bf16(v[2], v[3]); *(uint2*)p = w; }
; DEV float wave_sum(float v) {
; #pragma unroll
;     for (int o = 32; o >= 1; o >>= 1) v += __shfl_xor(v, o);
;     return v;
; }
; DEV float wave_max(float v) {
; #pragma unroll
;     for (int o = 32; o >= 1; o >>= 1) v = fmaxf(v, __shfl_xor(v, o));
;     return v;
; __global__ void __launch_bounds__(512) hymba_fwd(Params p) {
;     ...
;     for (int r = bid * 8 + wid; r < TP * 4; r += G * 8) {
;         const f32x4 v = __builtin_nontemporal_load((const f32x4*)(sc + (size_t)r * 256 + lane * 4));
;         const float mx = wave_max(fmaxf(fmaxf(v[0], v[1]), fmaxf(v[2], v[3])));
;         f32x4 e; e[0] = __expf(v[0] - mx); e[1] = __expf(v[1] - mx); e[2] = __expf(v[2] - mx); e[3] = __expf(v[3] - mx);
;         const float inv = 1.f / wave_sum(e[0] + e[1] + e[2] + e[3]);
;         store_bf4(pb + (size_t)(r >> 2) * LDP + (r & 3) * 256 + lane * 4, e * inv);
	v_add_f32_e32 v56, v56, v60
	s_waitcnt lgkmcnt(2)
	v_add_f32_e32 v57, v57, v61
	s_waitcnt lgkmcnt(1)
	v_add_f32_e32 v58, v58, v62
	s_waitcnt lgkmcnt(0)
	v_add_f32_e32 v59, v59, v63
	ds_bpermute_b32 v60, v11, v56
	ds_bpermute_b32 v61, v11, v57
	ds_bpermute_b32 v62, v11, v58
	ds_bpermute_b32 v63, v11, v59
	s_waitcnt lgkmcnt(3)
	v_add_f32_e32 v56, v56, v60
	s_waitcnt lgkmcnt(2)
	v_add_f32_e32 v57, v57, v61
	s_waitcnt lgkmcnt(1)
	v_add_f32_e32 v58, v58, v62
	s_waitcnt lgkmcnt(0)
	v_add_f32_e32 v59, v59, v63
	ds_bpermute_b32 v60, v12, v56
	ds_bpermute_b32 v61, v12, v57
	ds_bpermute_b32 v62, v12, v58
	ds_bpermute_b32 v63, v12, v59
	s_waitcnt lgkmcnt(3)
	v_add_f32_e32 v56, v56, v60
	s_waitcnt lgkmcnt(2)
	v_add_f32_e32 v57, v57, v61
	s_waitcnt lgkmcnt(1)
	v_add_f32_e32 v58, v58, v62
	s_waitcnt lgkmcnt(0)
	v_add_f32_e32 v59, v59, v63
	ds_bpermute_b32 v60, v13, v56
	ds_bpermute_b32 v61, v13, v57
	ds_bpermute_b32 v62, v13, v58
	ds_bpermute_b32 v63, v13, v59
	s_waitcnt lgkmcnt(3)
	v_add_f32_e32 v56, v56, v60
	s_waitcnt lgkmcnt(2)
	v_add_f32_e32 v57, v57, v61
	s_waitcnt lgkmcnt(1)
	v_add_f32_e32 v58, v58, v62
	s_waitcnt lgkmcnt(0)
	v_add_f32_e32 v59, v59, v63
	v_div_scale_f32 v64, s[16:17], v56, v56, 1.0
	v_rcp_f32_e32 v65, v64
	v_div_scale_f32 v66, vcc, 1.0, v56, 1.0
	v_fma_f32 v67, -v64, v65, 1.0
	v_fmac_f32_e32 v65, v67, v65
	v_mul_f32_e32 v67, v66, v65
	v_fma_f32 v68, -v64, v67, v66
	v_fmac_f32_e32 v67, v68, v65
	v_fma_f32 v64, -v64, v67, v66
	v_div_fmas_f32 v64, v64, v65, v67
	v_div_fixup_f32 v56, v64, v56, 1.0
	v_mul_f32_e32 v40, v40, v56
	v_mul_f32_e32 v41, v41, v56
	v_mul_f32_e32 v42, v42, v56
	v_mul_f32_e32 v43, v43, v56
	v_cvt_pk_bf16_f32 v40, v40, v41
	v_cvt_pk_bf16_f32 v41, v42, v43
	global_store_dwordx2 v[20:21], v[40:41], off
	v_lshl_add_u64 v[20:21], v[20:21], 0, s[10:11]
	v_div_scale_f32 v64, s[16:17], v57, v57, 1.0
	v_rcp_f32_e32 v65, v64
	v_div_scale_f32 v66, vcc, 1.0, v57, 1.0
	v_fma_f32 v67, -v64, v65, 1.0
	v_fmac_f32_e32 v65, v67, v65
	v_mul_f32_e32 v67, v66, v65
	v_fma_f32 v68, -v64, v67, v66
	v_fmac_f32_e32 v67, v68, v65
	v_fma_f32 v64, -v64, v67, v66
	v_div_fmas_f32 v64, v64, v65, v67
	v_div_fixup_f32 v57, v64, v57, 1.0
	v_mul_f32_e32 v44, v44, v57
	v_mul_f32_e32 v45, v45, v57
	v_mul_f32_e32 v46, v46, v57
	v_mul_f32_e32 v47, v47, v57
	v_cvt_pk_bf16_f32 v44, v44, v45
	v_cvt_pk_bf16_f32 v45, v46, v47
	global_store_dwordx2 v[20:21], v[44:45], off
	v_lshl_add_u64 v[20:21], v[20:21], 0, s[10:11]
	v_div_scale_f32 v64, s[16:17], v58, v58, 1.0
	v_rcp_f32_e32 v65, v64
	v_div_scale_f32 v66, vcc, 1.0, v58, 1.0
	v_fma_f32 v67, -v64, v65, 1.0
	v_fmac_f32_e32 v65, v67, v65
	v_mul_f32_e32 v67, v66, v65
	v_fma_f32 v68, -v64, v67, v66
	v_fmac_f32_e32 v67, v68, v65
	v_fma_f32 v64, -v64, v67, v66
	v_div_fmas_f32 v64, v64, v65, v67
	v_div_fixup_f32 v58, v64, v58, 1.0
	v_mul_f32_e32 v48, v48, v58
	v_mul_f32_e32 v49, v49, v58
	v_mul_f32_e32 v50, v50, v58
	v_mul_f32_e32 v51, v51, v58
	v_cvt_pk_bf16_f32 v48, v48, v49
	v_cvt_pk_bf16_f32 v49, v50, v51
	global_store_dwordx2 v[20:21], v[48:49], off
	v_lshl_add_u64 v[20:21], v[20:21], 0, s[10:11]
	v_div_scale_f32 v64, s[16:17], v59, v59, 1.0
	v_rcp_f32_e32 v65, v64
	v_div_scale_f32 v66, vcc, 1.0, v59, 1.0
	v_fma_f32 v67, -v64, v65, 1.0
	v_fmac_f32_e32 v65, v67, v65
	v_mul_f32_e32 v67, v66, v65
	v_fma_f32 v68, -v64, v67, v66
	v_fmac_f32_e32 v67, v68, v65
	v_fma_f32 v64, -v64, v67, v66
	v_div_fmas_f32 v64, v64, v65, v67
	v_div_fixup_f32 v59, v64, v59, 1.0
	v_mul_f32_e32 v52, v52, v59
	v_mul_f32_e32 v53, v53, v59
	v_mul_f32_e32 v54, v54, v59
	v_mul_f32_e32 v55, v55, v59
	v_cvt_pk_bf16_f32 v52, v52, v53
	v_cvt_pk_bf16_f32 v53, v54, v55
	global_store_dwordx2 v[20:21], v[52:53], off
	v_lshl_add_u64 v[20:21], v[20:21], 0, s[10:11]
	global_load_dwordx4 v[40:43], v[4:5], off nt
	v_lshl_add_u64 v[4:5], v[4:5], 0, s[8:9]
	global_load_dwordx4 v[44:47], v[4:5], off nt
	v_lshl_add_u64 v[4:5], v[4:5], 0, s[8:9]
	global_load_dwordx4 v[48:51], v[4:5], off nt
	v_lshl_add_u64 v[4:5], v[4:5], 0, s[8:9]
	global_load_dwordx4 v[52:55], v[4:5], off nt
	v_lshl_add_u64 v[4:5], v[4:5], 0, s[8:9]
	s_waitcnt vmcnt(8)
	v_max_f32_e32 v56, v27, v27
	v_max_f32_e32 v60, v26, v26
	v_max_f32_e32 v56, v60, v56
	v_max3_f32 v56, v24, v25, v56
	v_max_f32_e32 v57, v31, v31
	v_max_f32_e32 v61, v30, v30
	v_max_f32_e32 v57, v61, v57
	v_max3_f32 v57, v28, v29, v57
	v_max_f32_e32 v58, v35, v35
	v_max_f32_e32 v62, v34, v34
	v_max_f32_e32 v58, v62, v58
	v_max3_f32 v58, v32, v33, v58
	v_max_f32_e32 v59, v39, v39
	v_max_f32_e32 v63, v38, v38
	v_max_f32_e32 v59, v63, v59
	v_max3_f32 v59, v36, v37, v59
	ds_bpermute_b32 v60, v8, v56
	ds_bpermute_b32 v61, v8, v57
	ds_bpermute_b32 v62, v8, v58
	ds_bpermute_b32 v63, v8, v59
	s_waitcnt lgkmcnt(3)
	v_max_f32_e32 v60, v60, v60
	v_max_f32_e32 v56, v56, v60
	s_waitcnt lgkmcnt(2)
	v_max_f32_e32 v61, v61, v61
	v_max_f32_e32 v57, v57, v61
	s_waitcnt lgkmcnt(1)
	v_max_f32_e32 v62, v62, v62
	v_max_f32_e32 v58, v58, v62
	s_waitcnt lgkmcnt(0)
	v_max_f32_e32 v63, v63, v63
	v_max_f32_e32 v59, v59, v63
	ds_bpermute_b32 v60, v9, v56
	ds_bpermute_b32 v61, v9, v57
	ds_bpermute_b32 v62, v9, v58
	ds_bpermute_b32 v63, v9, v59
	s_waitcnt lgkmcnt(3)
	v_max_f32_e32 v60, v60, v60
	v_max_f32_e32 v56, v56, v60
	s_waitcnt lgkmcnt(2)
	v_max_f32_e32 v61, v61, v61
	v_max_f32_e32 v57, v57, v61
	s_waitcnt lgkmcnt(1)
	v_max_f32_e32 v62, v62, v62
	v_max_f32_e32 v58, v58, v62
	s_waitcnt lgkmcnt(0)
	v_max_f32_e32 v63, v63, v63
	v_max_f32_e32 v59, v59, v63
	ds_bpermute_b32 v60, v10, v56
	ds_bpermute_b32 v61, v10, v57
	ds_bpermute_b32 v62, v10, v58
	ds_bpermute_b32 v63, v10, v59
	s_waitcnt lgkmcnt(3)
	v_max_f32_e32 v60, v60, v60
	v_max_f32_e32 v56, v56, v60
	s_waitcnt lgkmcnt(2)
; DEV float wave_sum(float v) {
; #pragma unroll
;     for (int o = 32; o >= 1; o >>= 1) v += __shfl_xor(v, o);
;     return v;
; DEV float wave_max(float v) {
; #pragma unroll
;     for (int o = 32; o >= 1; o >>= 1) v = fmaxf(v, __shfl_xor(v, o));
;     return v;
; __global__ void __launch_bounds__(512) hymba_fwd(Params p) {
;     ...
;         const f32x4 v = __builtin_nontemporal_load((const f32x4*)(sc + (size_t)r * 256 + lane * 4));
;         const float mx = wave_max(fmaxf(fmaxf(v[0], v[1]), fmaxf(v[2], v[3])));
;         f32x4 e; e[0] = __expf(v[0] - mx); e[1] = __expf(v[1] - mx); e[2] = __expf(v[2] - mx); e[3] = __expf(v[3] - mx);
;         const float inv = 1.f / wave_sum(e[0] + e[1] + e[2] + e[3]);
	v_max_f32_e32 v61, v61, v61
	v_max_f32_e32 v57, v57, v61
	s_waitcnt lgkmcnt(1)
	v_max_f32_e32 v62, v62, v62
	v_max_f32_e32 v58, v58, v62
	s_waitcnt lgkmcnt(0)
	v_max_f32_e32 v63, v63, v63
	v_max_f32_e32 v59, v59, v63
	ds_bpermute_b32 v60, v11, v56
	ds_bpermute_b32 v61, v11, v57
	ds_bpermute_b32 v62, v11, v58
	ds_bpermute_b32 v63, v11, v59
	s_waitcnt lgkmcnt(3)
	v_max_f32_e32 v60, v60, v60
	v_max_f32_e32 v56, v56, v60
	s_waitcnt lgkmcnt(2)
	v_max_f32_e32 v61, v61, v61
	v_max_f32_e32 v57, v57, v61
	s_waitcnt lgkmcnt(1)
	v_max_f32_e32 v62, v62, v62
	v_max_f32_e32 v58, v58, v62
	s_waitcnt lgkmcnt(0)
	v_max_f32_e32 v63, v63, v63
	v_max_f32_e32 v59, v59, v63
	ds_bpermute_b32 v60, v12, v56
	ds_bpermute_b32 v61, v12, v57
	ds_bpermute_b32 v62, v12, v58
	ds_bpermute_b32 v63, v12, v59
	s_waitcnt lgkmcnt(3)
	v_max_f32_e32 v60, v60, v60
	v_max_f32_e32 v56, v56, v60
	s_waitcnt lgkmcnt(2)
	v_max_f32_e32 v61, v61, v61
	v_max_f32_e32 v57, v57, v61
	s_waitcnt lgkmcnt(1)
	v_max_f32_e32 v62, v62, v62
	v_max_f32_e32 v58, v58, v62
	s_waitcnt lgkmcnt(0)
	v_max_f32_e32 v63, v63, v63
	v_max_f32_e32 v59, v59, v63
	ds_bpermute_b32 v60, v13, v56
	ds_bpermute_b32 v61, v13, v57
	ds_bpermute_b32 v62, v13, v58
	ds_bpermute_b32 v63, v13, v59
	s_waitcnt lgkmcnt(3)
	v_max_f32_e32 v60, v60, v60
	v_max_f32_e32 v56, v56, v60
	s_waitcnt lgkmcnt(2)
	v_max_f32_e32 v61, v61, v61
	v_max_f32_e32 v57, v57, v61
	s_waitcnt lgkmcnt(1)
	v_max_f32_e32 v62, v62, v62
	v_max_f32_e32 v58, v58, v62
	s_waitcnt lgkmcnt(0)
	v_max_f32_e32 v63, v63, v63
	v_max_f32_e32 v59, v59, v63
	v_sub_f32_e32 v24, v24, v56
	v_sub_f32_e32 v25, v25, v56
	v_sub_f32_e32 v26, v26, v56
	v_sub_f32_e32 v27, v27, v56
	v_mul_f32_e32 v24, 0x3fb8aa3b, v24
	v_mul_f32_e32 v25, 0x3fb8aa3b, v25
	v_mul_f32_e32 v26, 0x3fb8aa3b, v26
	v_mul_f32_e32 v27, 0x3fb8aa3b, v27
	v_sub_f32_e32 v28, v28, v57
	v_sub_f32_e32 v29, v29, v57
	v_sub_f32_e32 v30, v30, v57
	v_sub_f32_e32 v31, v31, v57
	v_mul_f32_e32 v28, 0x3fb8aa3b, v28
	v_mul_f32_e32 v29, 0x3fb8aa3b, v29
	v_mul_f32_e32 v30, 0x3fb8aa3b, v30
	v_mul_f32_e32 v31, 0x3fb8aa3b, v31
	v_sub_f32_e32 v32, v32, v58
	v_sub_f32_e32 v33, v33, v58
	v_sub_f32_e32 v34, v34, v58
	v_sub_f32_e32 v35, v35, v58
	v_mul_f32_e32 v32, 0x3fb8aa3b, v32
	v_mul_f32_e32 v33, 0x3fb8aa3b, v33
	v_mul_f32_e32 v34, 0x3fb8aa3b, v34
	v_mul_f32_e32 v35, 0x3fb8aa3b, v35
	v_sub_f32_e32 v36, v36, v59
	v_sub_f32_e32 v37, v37, v59
	v_sub_f32_e32 v38, v38, v59
	v_sub_f32_e32 v39, v39, v59
	v_mul_f32_e32 v36, 0x3fb8aa3b, v36
	v_mul_f32_e32 v37, 0x3fb8aa3b, v37
	v_mul_f32_e32 v38, 0x3fb8aa3b, v38
	v_mul_f32_e32 v39, 0x3fb8aa3b, v39
	v_exp_f32_e32 v24, v24
	v_exp_f32_e32 v25, v25
	v_exp_f32_e32 v26, v26
	v_exp_f32_e32 v27, v27
	v_exp_f32_e32 v28, v28
	v_exp_f32_e32 v29, v29
	v_exp_f32_e32 v30, v30
	v_exp_f32_e32 v31, v31
	v_exp_f32_e32 v32, v32
	v_exp_f32_e32 v33, v33
	v_exp_f32_e32 v34, v34
	v_exp_f32_e32 v35, v35
	v_exp_f32_e32 v36, v36
	v_exp_f32_e32 v37, v37
	v_exp_f32_e32 v38, v38
	v_exp_f32_e32 v39, v39
	v_add_f32_e32 v56, v24, v25
	v_add_f32_e32 v56, v26, v56
	v_add_f32_e32 v56, v27, v56
	v_add_f32_e32 v57, v28, v29
	v_add_f32_e32 v57, v30, v57
	v_add_f32_e32 v57, v31, v57
	v_add_f32_e32 v58, v32, v33
	v_add_f32_e32 v58, v34, v58
	v_add_f32_e32 v58, v35, v58
	v_add_f32_e32 v59, v36, v37
	v_add_f32_e32 v59, v38, v59
	v_add_f32_e32 v59, v39, v59
	ds_bpermute_b32 v60, v8, v56
	ds_bpermute_b32 v61, v8, v57
	ds_bpermute_b32 v62, v8, v58
	ds_bpermute_b32 v63, v8, v59
	s_waitcnt lgkmcnt(3)
	v_add_f32_e32 v56, v56, v60
	s_waitcnt lgkmcnt(2)
	v_add_f32_e32 v57, v57, v61
	s_waitcnt lgkmcnt(1)
	v_add_f32_e32 v58, v58, v62
	s_waitcnt lgkmcnt(0)
	v_add_f32_e32 v59, v59, v63
	ds_bpermute_b32 v60, v9, v56
	ds_bpermute_b32 v61, v9, v57
	ds_bpermute_b32 v62, v9, v58
	ds_bpermute_b32 v63, v9, v59
	s_waitcnt lgkmcnt(3)
	v_add_f32_e32 v56, v56, v60
	s_waitcnt lgkmcnt(2)
	v_add_f32_e32 v57, v57, v61
	s_waitcnt lgkmcnt(1)
	v_add_f32_e32 v58, v58, v62
	s_waitcnt lgkmcnt(0)
	v_add_f32_e32 v59, v59, v63
	ds_bpermute_b32 v60, v10, v56
	ds_bpermute_b32 v61, v10, v57
	ds_bpermute_b32 v62, v10, v58
	ds_bpermute_b32 v63, v10, v59
	s_waitcnt lgkmcnt(3)
	v_add_f32_e32 v56, v56, v60
	s_waitcnt lgkmcnt(2)
	v_add_f32_e32 v57, v57, v61
	s_waitcnt lgkmcnt(1)
	v_add_f32_e32 v58, v58, v62
	s_waitcnt lgkmcnt(0)
	v_add_f32_e32 v59, v59, v63
	ds_bpermute_b32 v60, v11, v56
	ds_bpermute_b32 v61, v11, v57
	ds_bpermute_b32 v62, v11, v58
	ds_bpermute_b32 v63, v11, v59
	s_waitcnt lgkmcnt(3)
	v_add_f32_e32 v56, v56, v60
	s_waitcnt lgkmcnt(2)
	v_add_f32_e32 v57, v57, v61
	s_waitcnt lgkmcnt(1)
	v_add_f32_e32 v58, v58, v62
	s_waitcnt lgkmcnt(0)
	v_add_f32_e32 v59, v59, v63
	ds_bpermute_b32 v60, v12, v56
	ds_bpermute_b32 v61, v12, v57
	ds_bpermute_b32 v62, v12, v58
	ds_bpermute_b32 v63, v12, v59
	s_waitcnt lgkmcnt(3)
	v_add_f32_e32 v56, v56, v60
	s_waitcnt lgkmcnt(2)
	v_add_f32_e32 v57, v57, v61
	s_waitcnt lgkmcnt(1)
	v_add_f32_e32 v58, v58, v62
	s_waitcnt lgkmcnt(0)
	v_add_f32_e32 v59, v59, v63
	ds_bpermute_b32 v60, v13, v56
	ds_bpermute_b32 v61, v13, v57
	ds_bpermute_b32 v62, v13, v58
	ds_bpermute_b32 v63, v13, v59
	s_waitcnt lgkmcnt(3)
	v_add_f32_e32 v56, v56, v60
	s_waitcnt lgkmcnt(2)
	v_add_f32_e32 v57, v57, v61
	s_waitcnt lgkmcnt(1)
	v_add_f32_e32 v58, v58, v62
	s_waitcnt lgkmcnt(0)
; DEV void store_bf4(bf16_t* p, f32x4 v) { uint2 w; w.x = cvt_pk_bf16(v[0], v[1]); w.y = cvt_pk_bf16(v[2], v[3]); *(uint2*)p = w; }
; DEV float wave_max(float v) {
; #pragma unroll
;     for (int o = 32; o >= 1; o >>= 1) v = fmaxf(v, __shfl_xor(v, o));
;     return v;
; __global__ void __launch_bounds__(512) hymba_fwd(Params p) {
;     ...
;         f32x4 e; e[0] = __expf(v[0] - mx); e[1] = __expf(v[1] - mx); e[2] = __expf(v[2] - mx); e[3] = __expf(v[3] - mx);
;         const float inv = 1.f / wave_sum(e[0] + e[1] + e[2] + e[3]);
;         store_bf4(pb + (size_t)(r >> 2) * LDP + (r & 3) * 256 + lane * 4, e * inv);
	v_add_f32_e32 v59, v59, v63
	v_div_scale_f32 v64, s[16:17], v56, v56, 1.0
	v_rcp_f32_e32 v65, v64
	v_div_scale_f32 v66, vcc, 1.0, v56, 1.0
	v_fma_f32 v67, -v64, v65, 1.0
	v_fmac_f32_e32 v65, v67, v65
	v_mul_f32_e32 v67, v66, v65
	v_fma_f32 v68, -v64, v67, v66
	v_fmac_f32_e32 v67, v68, v65
	v_fma_f32 v64, -v64, v67, v66
	v_div_fmas_f32 v64, v64, v65, v67
	v_div_fixup_f32 v56, v64, v56, 1.0
	v_mul_f32_e32 v24, v24, v56
	v_mul_f32_e32 v25, v25, v56
	v_mul_f32_e32 v26, v26, v56
	v_mul_f32_e32 v27, v27, v56
	v_cvt_pk_bf16_f32 v24, v24, v25
	v_cvt_pk_bf16_f32 v25, v26, v27
	global_store_dwordx2 v[20:21], v[24:25], off
	v_lshl_add_u64 v[20:21], v[20:21], 0, s[10:11]
	v_div_scale_f32 v64, s[16:17], v57, v57, 1.0
	v_rcp_f32_e32 v65, v64
	v_div_scale_f32 v66, vcc, 1.0, v57, 1.0
	v_fma_f32 v67, -v64, v65, 1.0
	v_fmac_f32_e32 v65, v67, v65
	v_mul_f32_e32 v67, v66, v65
	v_fma_f32 v68, -v64, v67, v66
	v_fmac_f32_e32 v67, v68, v65
	v_fma_f32 v64, -v64, v67, v66
	v_div_fmas_f32 v64, v64, v65, v67
	v_div_fixup_f32 v57, v64, v57, 1.0
	v_mul_f32_e32 v28, v28, v57
	v_mul_f32_e32 v29, v29, v57
	v_mul_f32_e32 v30, v30, v57
	v_mul_f32_e32 v31, v31, v57
	v_cvt_pk_bf16_f32 v28, v28, v29
	v_cvt_pk_bf16_f32 v29, v30, v31
	global_store_dwordx2 v[20:21], v[28:29], off
	v_lshl_add_u64 v[20:21], v[20:21], 0, s[10:11]
	v_div_scale_f32 v64, s[16:17], v58, v58, 1.0
	v_rcp_f32_e32 v65, v64
	v_div_scale_f32 v66, vcc, 1.0, v58, 1.0
	v_fma_f32 v67, -v64, v65, 1.0
	v_fmac_f32_e32 v65, v67, v65
	v_mul_f32_e32 v67, v66, v65
	v_fma_f32 v68, -v64, v67, v66
	v_fmac_f32_e32 v67, v68, v65
	v_fma_f32 v64, -v64, v67, v66
	v_div_fmas_f32 v64, v64, v65, v67
	v_div_fixup_f32 v58, v64, v58, 1.0
	v_mul_f32_e32 v32, v32, v58
	v_mul_f32_e32 v33, v33, v58
	v_mul_f32_e32 v34, v34, v58
	v_mul_f32_e32 v35, v35, v58
	v_cvt_pk_bf16_f32 v32, v32, v33
	v_cvt_pk_bf16_f32 v33, v34, v35
	global_store_dwordx2 v[20:21], v[32:33], off
	v_lshl_add_u64 v[20:21], v[20:21], 0, s[10:11]
	v_div_scale_f32 v64, s[16:17], v59, v59, 1.0
	v_rcp_f32_e32 v65, v64
	v_div_scale_f32 v66, vcc, 1.0, v59, 1.0
	v_fma_f32 v67, -v64, v65, 1.0
	v_fmac_f32_e32 v65, v67, v65
	v_mul_f32_e32 v67, v66, v65
	v_fma_f32 v68, -v64, v67, v66
	v_fmac_f32_e32 v67, v68, v65
	v_fma_f32 v64, -v64, v67, v66
	v_div_fmas_f32 v64, v64, v65, v67
	v_div_fixup_f32 v59, v64, v59, 1.0
	v_mul_f32_e32 v36, v36, v59
	v_mul_f32_e32 v37, v37, v59
	v_mul_f32_e32 v38, v38, v59
	v_mul_f32_e32 v39, v39, v59
	v_cvt_pk_bf16_f32 v36, v36, v37
	v_cvt_pk_bf16_f32 v37, v38, v39
	global_store_dwordx2 v[20:21], v[36:37], off
	v_lshl_add_u64 v[20:21], v[20:21], 0, s[10:11]
	s_waitcnt vmcnt(4)
	v_max_f32_e32 v56, v43, v43
	v_max_f32_e32 v60, v42, v42
	v_max_f32_e32 v56, v60, v56
	v_max3_f32 v56, v40, v41, v56
	v_max_f32_e32 v57, v47, v47
	v_max_f32_e32 v61, v46, v46
	v_max_f32_e32 v57, v61, v57
	v_max3_f32 v57, v44, v45, v57
	v_max_f32_e32 v58, v51, v51
	v_max_f32_e32 v62, v50, v50
	v_max_f32_e32 v58, v62, v58
	v_max3_f32 v58, v48, v49, v58
	v_max_f32_e32 v59, v55, v55
	v_max_f32_e32 v63, v54, v54
	v_max_f32_e32 v59, v63, v59
	v_max3_f32 v59, v52, v53, v59
	ds_bpermute_b32 v60, v8, v56
	ds_bpermute_b32 v61, v8, v57
	ds_bpermute_b32 v62, v8, v58
	ds_bpermute_b32 v63, v8, v59
	s_waitcnt lgkmcnt(3)
	v_max_f32_e32 v60, v60, v60
	v_max_f32_e32 v56, v56, v60
	s_waitcnt lgkmcnt(2)
	v_max_f32_e32 v61, v61, v61
	v_max_f32_e32 v57, v57, v61
	s_waitcnt lgkmcnt(1)
	v_max_f32_e32 v62, v62, v62
	v_max_f32_e32 v58, v58, v62
	s_waitcnt lgkmcnt(0)
	v_max_f32_e32 v63, v63, v63
	v_max_f32_e32 v59, v59, v63
	ds_bpermute_b32 v60, v9, v56
	ds_bpermute_b32 v61, v9, v57
	ds_bpermute_b32 v62, v9, v58
	ds_bpermute_b32 v63, v9, v59
	s_waitcnt lgkmcnt(3)
	v_max_f32_e32 v60, v60, v60
	v_max_f32_e32 v56, v56, v60
	s_waitcnt lgkmcnt(2)
	v_max_f32_e32 v61, v61, v61
	v_max_f32_e32 v57, v57, v61
	s_waitcnt lgkmcnt(1)
	v_max_f32_e32 v62, v62, v62
	v_max_f32_e32 v58, v58, v62
	s_waitcnt lgkmcnt(0)
	v_max_f32_e32 v63, v63, v63
	v_max_f32_e32 v59, v59, v63
	ds_bpermute_b32 v60, v10, v56
	ds_bpermute_b32 v61, v10, v57
	ds_bpermute_b32 v62, v10, v58
	ds_bpermute_b32 v63, v10, v59
	s_waitcnt lgkmcnt(3)
	v_max_f32_e32 v60, v60, v60
	v_max_f32_e32 v56, v56, v60
	s_waitcnt lgkmcnt(2)
	v_max_f32_e32 v61, v61, v61
	v_max_f32_e32 v57, v57, v61
	s_waitcnt lgkmcnt(1)
	v_max_f32_e32 v62, v62, v62
	v_max_f32_e32 v58, v58, v62
	s_waitcnt lgkmcnt(0)
	v_max_f32_e32 v63, v63, v63
	v_max_f32_e32 v59, v59, v63
	ds_bpermute_b32 v60, v11, v56
	ds_bpermute_b32 v61, v11, v57
	ds_bpermute_b32 v62, v11, v58
	ds_bpermute_b32 v63, v11, v59
	s_waitcnt lgkmcnt(3)
	v_max_f32_e32 v60, v60, v60
	v_max_f32_e32 v56, v56, v60
	s_waitcnt lgkmcnt(2)
	v_max_f32_e32 v61, v61, v61
	v_max_f32_e32 v57, v57, v61
	s_waitcnt lgkmcnt(1)
	v_max_f32_e32 v62, v62, v62
	v_max_f32_e32 v58, v58, v62
	s_waitcnt lgkmcnt(0)
	v_max_f32_e32 v63, v63, v63
	v_max_f32_e32 v59, v59, v63
	ds_bpermute_b32 v60, v12, v56
	ds_bpermute_b32 v61, v12, v57
	ds_bpermute_b32 v62, v12, v58
	ds_bpermute_b32 v63, v12, v59
	s_waitcnt lgkmcnt(3)
	v_max_f32_e32 v60, v60, v60
	v_max_f32_e32 v56, v56, v60
	s_waitcnt lgkmcnt(2)
	v_max_f32_e32 v61, v61, v61
	v_max_f32_e32 v57, v57, v61
	s_waitcnt lgkmcnt(1)
	v_max_f32_e32 v62, v62, v62
	v_max_f32_e32 v58, v58, v62
	s_waitcnt lgkmcnt(0)
	v_max_f32_e32 v63, v63, v63
	v_max_f32_e32 v59, v59, v63
	ds_bpermute_b32 v60, v13, v56
	ds_bpermute_b32 v61, v13, v57
	ds_bpermute_b32 v62, v13, v58
	ds_bpermute_b32 v63, v13, v59
	s_waitcnt lgkmcnt(3)
	v_max_f32_e32 v60, v60, v60
	v_max_f32_e32 v56, v56, v60
	s_waitcnt lgkmcnt(2)
	v_max_f32_e32 v61, v61, v61
	v_max_f32_e32 v57, v57, v61
	s_waitcnt lgkmcnt(1)
	v_max_f32_e32 v62, v62, v62
	v_max_f32_e32 v58, v58, v62
	s_waitcnt lgkmcnt(0)
; DEV void store_bf4(bf16_t* p, f32x4 v) { uint2 w; w.x = cvt_pk_bf16(v[0], v[1]); w.y = cvt_pk_bf16(v[2], v[3]); *(uint2*)p = w; }
; DEV float wave_sum(float v) {
; #pragma unroll
;     for (int o = 32; o >= 1; o >>= 1) v += __shfl_xor(v, o);
;     return v;
; __global__ void __launch_bounds__(512) hymba_fwd(Params p) {
;     ...
;         const float mx = wave_max(fmaxf(fmaxf(v[0], v[1]), fmaxf(v[2], v[3])));
;         f32x4 e; e[0] = __expf(v[0] - mx); e[1] = __expf(v[1] - mx); e[2] = __expf(v[2] - mx); e[3] = __expf(v[3] - mx);
;         const float inv = 1.f / wave_sum(e[0] + e[1] + e[2] + e[3]);
;         store_bf4(pb + (size_t)(r >> 2) * LDP + (r & 3) * 256 + lane * 4, e * inv);
	v_max_f32_e32 v63, v63, v63
	v_max_f32_e32 v59, v59, v63
	v_sub_f32_e32 v40, v40, v56
	v_sub_f32_e32 v41, v41, v56
	v_sub_f32_e32 v42, v42, v56
	v_sub_f32_e32 v43, v43, v56
	v_mul_f32_e32 v40, 0x3fb8aa3b, v40
	v_mul_f32_e32 v41, 0x3fb8aa3b, v41
	v_mul_f32_e32 v42, 0x3fb8aa3b, v42
	v_mul_f32_e32 v43, 0x3fb8aa3b, v43
	v_sub_f32_e32 v44, v44, v57
	v_sub_f32_e32 v45, v45, v57
	v_sub_f32_e32 v46, v46, v57
	v_sub_f32_e32 v47, v47, v57
	v_mul_f32_e32 v44, 0x3fb8aa3b, v44
	v_mul_f32_e32 v45, 0x3fb8aa3b, v45
	v_mul_f32_e32 v46, 0x3fb8aa3b, v46
	v_mul_f32_e32 v47, 0x3fb8aa3b, v47
	v_sub_f32_e32 v48, v48, v58
	v_sub_f32_e32 v49, v49, v58
	v_sub_f32_e32 v50, v50, v58
	v_sub_f32_e32 v51, v51, v58
	v_mul_f32_e32 v48, 0x3fb8aa3b, v48
	v_mul_f32_e32 v49, 0x3fb8aa3b, v49
	v_mul_f32_e32 v50, 0x3fb8aa3b, v50
	v_mul_f32_e32 v51, 0x3fb8aa3b, v51
	v_sub_f32_e32 v52, v52, v59
	v_sub_f32_e32 v53, v53, v59
	v_sub_f32_e32 v54, v54, v59
	v_sub_f32_e32 v55, v55, v59
	v_mul_f32_e32 v52, 0x3fb8aa3b, v52
	v_mul_f32_e32 v53, 0x3fb8aa3b, v53
	v_mul_f32_e32 v54, 0x3fb8aa3b, v54
	v_mul_f32_e32 v55, 0x3fb8aa3b, v55
	v_exp_f32_e32 v40, v40
	v_exp_f32_e32 v41, v41
	v_exp_f32_e32 v42, v42
	v_exp_f32_e32 v43, v43
	v_exp_f32_e32 v44, v44
	v_exp_f32_e32 v45, v45
	v_exp_f32_e32 v46, v46
	v_exp_f32_e32 v47, v47
	v_exp_f32_e32 v48, v48
	v_exp_f32_e32 v49, v49
	v_exp_f32_e32 v50, v50
	v_exp_f32_e32 v51, v51
	v_exp_f32_e32 v52, v52
	v_exp_f32_e32 v53, v53
	v_exp_f32_e32 v54, v54
	v_exp_f32_e32 v55, v55
	v_add_f32_e32 v56, v40, v41
	v_add_f32_e32 v56, v42, v56
	v_add_f32_e32 v56, v43, v56
	v_add_f32_e32 v57, v44, v45
	v_add_f32_e32 v57, v46, v57
	v_add_f32_e32 v57, v47, v57
	v_add_f32_e32 v58, v48, v49
	v_add_f32_e32 v58, v50, v58
	v_add_f32_e32 v58, v51, v58
	v_add_f32_e32 v59, v52, v53
	v_add_f32_e32 v59, v54, v59
	v_add_f32_e32 v59, v55, v59
	ds_bpermute_b32 v60, v8, v56
	ds_bpermute_b32 v61, v8, v57
	ds_bpermute_b32 v62, v8, v58
	ds_bpermute_b32 v63, v8, v59
	s_waitcnt lgkmcnt(3)
	v_add_f32_e32 v56, v56, v60
	s_waitcnt lgkmcnt(2)
	v_add_f32_e32 v57, v57, v61
	s_waitcnt lgkmcnt(1)
	v_add_f32_e32 v58, v58, v62
	s_waitcnt lgkmcnt(0)
	v_add_f32_e32 v59, v59, v63
	ds_bpermute_b32 v60, v9, v56
	ds_bpermute_b32 v61, v9, v57
	ds_bpermute_b32 v62, v9, v58
	ds_bpermute_b32 v63, v9, v59
	s_waitcnt lgkmcnt(3)
	v_add_f32_e32 v56, v56, v60
	s_waitcnt lgkmcnt(2)
	v_add_f32_e32 v57, v57, v61
	s_waitcnt lgkmcnt(1)
	v_add_f32_e32 v58, v58, v62
	s_waitcnt lgkmcnt(0)
	v_add_f32_e32 v59, v59, v63
	ds_bpermute_b32 v60, v10, v56
	ds_bpermute_b32 v61, v10, v57
	ds_bpermute_b32 v62, v10, v58
	ds_bpermute_b32 v63, v10, v59
	s_waitcnt lgkmcnt(3)
	v_add_f32_e32 v56, v56, v60
	s_waitcnt lgkmcnt(2)
	v_add_f32_e32 v57, v57, v61
	s_waitcnt lgkmcnt(1)
	v_add_f32_e32 v58, v58, v62
	s_waitcnt lgkmcnt(0)
	v_add_f32_e32 v59, v59, v63
	ds_bpermute_b32 v60, v11, v56
	ds_bpermute_b32 v61, v11, v57
	ds_bpermute_b32 v62, v11, v58
	ds_bpermute_b32 v63, v11, v59
	s_waitcnt lgkmcnt(3)
	v_add_f32_e32 v56, v56, v60
	s_waitcnt lgkmcnt(2)
	v_add_f32_e32 v57, v57, v61
	s_waitcnt lgkmcnt(1)
	v_add_f32_e32 v58, v58, v62
	s_waitcnt lgkmcnt(0)
	v_add_f32_e32 v59, v59, v63
	ds_bpermute_b32 v60, v12, v56
	ds_bpermute_b32 v61, v12, v57
	ds_bpermute_b32 v62, v12, v58
	ds_bpermute_b32 v63, v12, v59
	s_waitcnt lgkmcnt(3)
	v_add_f32_e32 v56, v56, v60
	s_waitcnt lgkmcnt(2)
	v_add_f32_e32 v57, v57, v61
	s_waitcnt lgkmcnt(1)
	v_add_f32_e32 v58, v58, v62
	s_waitcnt lgkmcnt(0)
	v_add_f32_e32 v59, v59, v63
	ds_bpermute_b32 v60, v13, v56
	ds_bpermute_b32 v61, v13, v57
	ds_bpermute_b32 v62, v13, v58
	ds_bpermute_b32 v63, v13, v59
	s_waitcnt lgkmcnt(3)
	v_add_f32_e32 v56, v56, v60
	s_waitcnt lgkmcnt(2)
	v_add_f32_e32 v57, v57, v61
	s_waitcnt lgkmcnt(1)
	v_add_f32_e32 v58, v58, v62
	s_waitcnt lgkmcnt(0)
	v_add_f32_e32 v59, v59, v63
	v_div_scale_f32 v64, s[16:17], v56, v56, 1.0
	v_rcp_f32_e32 v65, v64
	v_div_scale_f32 v66, vcc, 1.0, v56, 1.0
	v_fma_f32 v67, -v64, v65, 1.0
	v_fmac_f32_e32 v65, v67, v65
	v_mul_f32_e32 v67, v66, v65
	v_fma_f32 v68, -v64, v67, v66
	v_fmac_f32_e32 v67, v68, v65
	v_fma_f32 v64, -v64, v67, v66
	v_div_fmas_f32 v64, v64, v65, v67
	v_div_fixup_f32 v56, v64, v56, 1.0
	v_mul_f32_e32 v40, v40, v56
	v_mul_f32_e32 v41, v41, v56
	v_mul_f32_e32 v42, v42, v56
	v_mul_f32_e32 v43, v43, v56
	v_cvt_pk_bf16_f32 v40, v40, v41
	v_cvt_pk_bf16_f32 v41, v42, v43
	global_store_dwordx2 v[20:21], v[40:41], off
	v_lshl_add_u64 v[20:21], v[20:21], 0, s[10:11]
	v_div_scale_f32 v64, s[16:17], v57, v57, 1.0
	v_rcp_f32_e32 v65, v64
	v_div_scale_f32 v66, vcc, 1.0, v57, 1.0
	v_fma_f32 v67, -v64, v65, 1.0
	v_fmac_f32_e32 v65, v67, v65
	v_mul_f32_e32 v67, v66, v65
	v_fma_f32 v68, -v64, v67, v66
	v_fmac_f32_e32 v67, v68, v65
	v_fma_f32 v64, -v64, v67, v66
	v_div_fmas_f32 v64, v64, v65, v67
	v_div_fixup_f32 v57, v64, v57, 1.0
	v_mul_f32_e32 v44, v44, v57
	v_mul_f32_e32 v45, v45, v57
	v_mul_f32_e32 v46, v46, v57
	v_mul_f32_e32 v47, v47, v57
	v_cvt_pk_bf16_f32 v44, v44, v45
	v_cvt_pk_bf16_f32 v45, v46, v47
	global_store_dwordx2 v[20:21], v[44:45], off
	v_lshl_add_u64 v[20:21], v[20:21], 0, s[10:11]
	v_div_scale_f32 v64, s[16:17], v58, v58, 1.0
	v_rcp_f32_e32 v65, v64
	v_div_scale_f32 v66, vcc, 1.0, v58, 1.0
	v_fma_f32 v67, -v64, v65, 1.0
	v_fmac_f32_e32 v65, v67, v65
	v_mul_f32_e32 v67, v66, v65
	v_fma_f32 v68, -v64, v67, v66
	v_fmac_f32_e32 v67, v68, v65
	v_fma_f32 v64, -v64, v67, v66
	v_div_fmas_f32 v64, v64, v65, v67
	v_div_fixup_f32 v58, v64, v58, 1.0
	v_mul_f32_e32 v48, v48, v58
	v_mul_f32_e32 v49, v49, v58
	v_mul_f32_e32 v50, v50, v58
	v_mul_f32_e32 v51, v51, v58
	v_cvt_pk_bf16_f32 v48, v48, v49
	v_cvt_pk_bf16_f32 v49, v50, v51
	global_store_dwordx2 v[20:21], v[48:49], off
	v_lshl_add_u64 v[20:21], v[20:21], 0, s[10:11]
	v_div_scale_f32 v64, s[16:17], v59, v59, 1.0
	v_rcp_f32_e32 v65, v64
	v_div_scale_f32 v66, vcc, 1.0, v59, 1.0
	v_fma_f32 v67, -v64, v65, 1.0
	v_fmac_f32_e32 v65, v67, v65
	v_mul_f32_e32 v67, v66, v65
	v_fma_f32 v68, -v64, v67, v66
	v_fmac_f32_e32 v67, v68, v65
	v_fma_f32 v64, -v64, v67, v66
	v_div_fmas_f32 v64, v64, v65, v67
	v_div_fixup_f32 v59, v64, v59, 1.0
	v_mul_f32_e32 v52, v52, v59
	v_mul_f32_e32 v53, v53, v59
	v_mul_f32_e32 v54, v54, v59
	v_mul_f32_e32 v55, v55, v59
	v_cvt_pk_bf16_f32 v52, v52, v53
	v_cvt_pk_bf16_f32 v53, v54, v55
	global_store_dwordx2 v[20:21], v[52:53], off
	v_lshl_add_u64 v[20:21], v[20:21], 0, s[10:11]

; DEV void store_bf4(bf16_t* p, f32x4 v) { uint2 w; w.x = cvt_pk_bf16(v[0], v[1]); w.y = cvt_pk_bf16(v[2], v[3]); *(uint2*)p = w; }
; #define GRID_BAR() do { if (NLAUNCH == 1) xcd_barrier(bar); } while (0)
; DEV void xcd_barrier(const XcdBarrier& b) {
;     ...
;     __syncthreads();
; __global__ void __launch_bounds__(512) hymba_fwd(Params p) {
;     ...
;     GRID_BAR();
;     if (IN_PH(9)) { PH_LOCALS
;     for (int r = bid * 8 + wid; r < TP * 4; r += G * 8) {
;         const f32x4 v = __builtin_nontemporal_load((const f32x4*)(sc + (size_t)r * 256 + lane * 4));
;         const float mx = wave_max(fmaxf(fmaxf(v[0], v[1]), fmaxf(v[2], v[3])));
;         f32x4 e; e[0] = __expf(v[0] - mx); e[1] = __expf(v[1] - mx); e[2] = __expf(v[2] - mx); e[3] = __expf(v[3] - mx);
;         const float inv = 1.f / wave_sum(e[0] + e[1] + e[2] + e[3]);
;         store_bf4(pb + (size_t)(r >> 2) * LDP + (r & 3) * 256 + lane * 4, e * inv);
.LBB0_1349:
	s_or_b64 exec, exec, s[4:5]
	s_waitcnt lgkmcnt(0)
	s_barrier
	s_load_dwordx2 s[4:5], s[0:1], 0xd0
	s_mov_b64 s[6:7], 0x20f39000
	v_lshl_add_u64 v[86:87], v[158:159], 0, s[6:7]
	s_waitcnt lgkmcnt(0)
	s_cmp_lt_i32 s4, 10
	s_cselect_b64 s[8:9], -1, 0
	s_cmp_gt_i32 s5, 9
	s_cselect_b64 s[4:5], -1, 0
	s_and_b64 s[4:5], s[8:9], s[4:5]
	s_andn2_b64 vcc, exec, s[4:5]
	s_cmpk_eq_i32 s33, 0x100
	s_cbranch_scc1 .Lskip_p9
	s_cbranch_vccnz .LBB0_1354
	v_mov_b32_e32 v2, v0
	s_lshl_b32 s8, s2, 3
	v_ashrrev_i32_e32 v6, 6, v2
	v_add_u32_e32 v1, s8, v6
	s_mov_b32 s4, 0x8000
	v_cmp_gt_i32_e32 vcc, s4, v1
	s_and_saveexec_b64 s[4:5], vcc
	s_cbranch_execz .LBB0_1353
	v_mbcnt_lo_u32_b32 v4, -1, 0
	v_mbcnt_hi_u32_b32 v4, -1, v4
	v_and_b32_e32 v5, 64, v4
	v_add_u32_e32 v5, 64, v5
	v_xor_b32_e32 v7, 32, v4
	v_cmp_lt_i32_e32 vcc, v7, v5
	s_ashr_i32 s9, s8, 31
	v_lshlrev_b32_e32 v3, 2, v2
	v_cndmask_b32_e32 v7, v4, v7, vcc
	v_lshlrev_b32_e32 v8, 2, v7
	v_xor_b32_e32 v7, 16, v4
	v_cmp_lt_i32_e32 vcc, v7, v5
	v_and_b32_e32 v2, 63, v2
	s_lshl_b32 s6, s33, 3
	v_cndmask_b32_e32 v7, v4, v7, vcc
	v_lshlrev_b32_e32 v9, 2, v7
	v_xor_b32_e32 v7, 8, v4
	v_cmp_lt_i32_e32 vcc, v7, v5
	v_and_b32_e32 v16, 0xfc, v3
	v_mov_b32_e32 v3, 0
	v_cndmask_b32_e32 v7, v4, v7, vcc
	v_lshlrev_b32_e32 v10, 2, v7
	v_xor_b32_e32 v7, 4, v4
	v_cmp_lt_i32_e32 vcc, v7, v5
	s_ashr_i32 s7, s6, 31
	s_mov_b64 s[10:11], 0
	v_cndmask_b32_e32 v7, v4, v7, vcc
	v_lshlrev_b32_e32 v11, 2, v7
	v_xor_b32_e32 v7, 2, v4
	v_cmp_lt_i32_e32 vcc, v7, v5
	s_movk_i32 s12, 0x880
	s_movk_i32 s13, 0x7fff
	v_cndmask_b32_e32 v7, v4, v7, vcc
	v_lshlrev_b32_e32 v12, 2, v7
	v_xor_b32_e32 v7, 1, v4
	v_cmp_lt_i32_e32 vcc, v7, v5
	s_nop 1
	v_cndmask_b32_e32 v4, v4, v7, vcc
	v_ashrrev_i32_e32 v7, 31, v6
	v_lshlrev_b32_e32 v13, 2, v4
	v_lshl_add_u64 v[4:5], v[6:7], 0, s[8:9]
	v_lshlrev_b64 v[4:5], 10, v[4:5]
	v_lshl_or_b32 v4, v2, 4, v4
	v_lshl_add_u64 v[4:5], v[158:159], 0, v[4:5]
	s_mov_b64 s[8:9], 0x1ef39000
	v_lshlrev_b32_e32 v2, 8, v6
	v_lshl_add_u64 v[4:5], v[4:5], 0, s[8:9]
	s_lshl_b64 s[8:9], s[6:7], 10
	v_lshl_add_u32 v14, s2, 11, v2
	s_lshl_b32 s7, s33, 11
	v_lshlrev_b32_e32 v6, 1, v16
	v_mov_b32_e32 v7, v3

; #define VLOOP(t, N) for (int t##0_ = 2 * bid, t = min(t##0_ + vb, (N) - 1); t##0_ < (N); t##0_ += VG, t = min(t##0_ + vb, (N) - 1))
; __global__ void __launch_bounds__(512) hymba_fwd(Params p) {
;     ...
;     if (IN_PH(10)) { PH_LOCALS
;         VLOOP(t, 16 * 16 * 4) { const int bhd = t >> 6, v = t & 63, mt = v >> 2, nt = v & 3, b = bhd >> 2, hd = bhd & 3;
;             EpiBfS e{ctx + (size_t)(b * SEQ + mt * 128) * LDB + hd * 512 + nt * 128, LDB};
;             gemm_tile<64>(pb + (size_t)(b * SEQ + mt * 128) * LDP + hd * 256, LDP, mvt + ((size_t)b * D + hd * 512 + nt * 128) * LDM, LDM, 256, vlds, e);
.Lskip_p9:
	s_load_dwordx2 s[4:5], s[0:1], 0xd0
	s_mov_b64 s[6:7], 0x22039000
	v_lshl_add_u64 v[132:133], v[158:159], 0, s[6:7]
	s_waitcnt lgkmcnt(0)
	s_cmp_lt_i32 s4, 11
	s_cselect_b64 s[8:9], -1, 0
	s_cmp_gt_i32 s5, 10
	s_cselect_b64 s[4:5], -1, 0
	s_and_b64 s[4:5], s[8:9], s[4:5]
	s_andn2_b64 vcc, exec, s[4:5]
	s_cbranch_vccnz .LBB0_1410
	v_mov_b32_e32 v1, v0
	s_cmpk_gt_i32 s2, 0x1ff
	v_readfirstlane_b32 s4, v1
	s_cbranch_scc1 .LBB0_1410
	s_ashr_i32 s72, s4, 8
	s_lshl_b32 s74, s2, 1
	s_lshl_b32 s70, s72, 16
	s_add_i32 s4, s72, s74
	s_min_i32 s88, s4, 0x3ff
	v_and_b32_e32 v1, 0xff, v0
	s_or_b32 s71, s70, 0x8000
	s_add_i32 s72, s72, s75
	s_movk_i32 s73, 0x1080
	v_mov_b32_e32 v94, 0x1080
	s_mov_b32 s5, 0
	s_movk_i32 s76, 0x880
	v_mov_b32_e32 v95, 0x880
	s_movk_i32 s77, 0x240
	v_mov_b32_e32 v96, 0x240
	v_mov_b32_e32 v89, 0
	s_mov_b64 s[6:7], 0x11000
	s_mov_b64 s[8:9], 0x4800
	s_mov_b64 s[10:11], 0x22000
	s_mov_b64 s[12:13], 0x9000
	s_mov_b64 s[16:17], 0x33000
	s_mov_b64 s[18:19], 0xd800
	s_movk_i32 s78, 0xffc0
	s_mov_b64 s[20:21], 0x80
	s_mov_b64 s[22:23], 0x11080
	s_mov_b64 s[24:25], 0x4880
	s_mov_b64 s[26:27], 0x22080
	s_mov_b64 s[30:31], 0x9080
	s_mov_b64 s[34:35], 0x33080
	s_mov_b64 s[36:37], 0xd880
	s_mov_b64 s[38:39], 0x100
	s_mov_b64 s[40:41], 0x11100
	s_mov_b64 s[42:43], 0x4900
	s_mov_b64 s[44:45], 0x22100
	s_mov_b64 s[46:47], 0x9100
	s_mov_b64 s[48:49], 0x33100
	s_mov_b64 s[50:51], 0xd900
	s_mov_b64 s[52:53], 0x180
	s_mov_b64 s[54:55], 0x11180
	s_mov_b64 s[56:57], 0x4980
	s_mov_b64 s[58:59], 0x22180
	s_mov_b64 s[60:61], 0x9180
	s_mov_b64 s[62:63], 0x33180
	s_mov_b64 s[64:65], 0xd980
